# ret_out A_ret loads/stores and weight-conversion stores rearranged so every instruction covers 64 contiguous bytes per row (probe: -4.9 us per ret_out phase)
# speedup vs baseline: 1.0143x; 1.0077x over previous
; #define LAS __attribute__((address_space(3)))
; __device__ __forceinline__ void ret_out_phase(const Args& A, Frame& F, int l, bool lastl, bf16_t* ARET, bf16_t* ALRU) {
;     ...
;     for (int jx = 0; jx < nmy; ++jx) {
;         const int it = F.bid + jx * F.G, itn = (jx + 1 < nmy) ? it + F.G : it;
;         const int bh = it / NCHU, mc = it - bh * NCHU + (NCH - NCHU), h = bh & 7, b = bh >> 3;
;         const size_t rowbase = (size_t)b * TB + 128 * mc;
;         __syncthreads();
; #pragma unroll
;         for (int i = 0; i < 2; ++i) {
;             const int u = tid + i * NTHREADS, r = u >> 3, c8 = (u & 7) * 8;
;             *(LAS u32x4*)(ks_ + r * 72 + c8) = P.k[i]; *(LAS u32x4*)(sfs + r * 72 + c8) = P.sf[i]; *(LAS u32x4*)(sbs + r * 72 + c8) = P.sb[i];
;         }
; #pragma unroll
;         for (int i = 0; i < 4; ++i) { const int u = tid + i * NTHREADS, r = u >> 4, c8 = (u & 15) * 8; *(LAS u32x4*)(vts + r * 136 + c8) = P.vt[i]; }
;         bf16x8 qf[2];
; #pragma unroll
;         for (int ks = 0; ks < 2; ++ks) qf[ks] = *(const bf16x8*)(WSB(WS_Q) + (rowbase + 16 * w + fr) * 512 + h * 64 + 32 * ks + 8 * fq);
;         __syncthreads();
;         ret_prefetch(F, itn, NCHU, P);
;         const float l2f = log2_gamma(A, F, l, 0, h), l2b = log2_gamma(A, F, l, 1, h);
.LBB0_30:
	s_add_i32 s39, s39, 1
	s_cmp_lt_i32 s39, s37
	s_cselect_b32 s2, s34, 0
	s_abs_i32 s5, vcc_hi
	s_mul_hi_u32 s8, s5, s45
	s_mul_i32 s9, s8, s20
	s_sub_i32 s5, s5, s9
	s_ashr_i32 s4, vcc_hi, 31
	s_add_i32 s9, s8, 1
	s_sub_i32 s25, s5, s20
	s_cmp_ge_u32 s5, s20
	s_cselect_b32 s8, s9, s8
	s_cselect_b32 s5, s25, s5
	s_add_i32 s9, s8, 1
	s_cmp_ge_u32 s5, s20
	s_cselect_b32 s5, s9, s8
	s_xor_b32 s5, s5, s4
	s_sub_i32 s4, s5, s4
	s_not_b32 s5, s4
	s_mul_i32 s5, vcc_lo, s5
	s_ashr_i32 s8, s4, 3
	s_add_i32 s5, s61, s5
	s_ashr_i32 s9, s5, 31
	s_add_i32 s25, s2, vcc_hi
	s_mul_hi_i32 s52, s8, 0x900
	s_mulk_i32 s8, 0x900
	s_and_b32 s2, s4, 7
	s_add_u32 s8, s8, s5
	s_addc_u32 s9, s52, s9
	s_abs_i32 s5, s25
	s_mul_hi_u32 s52, s5, s45
	s_mul_i32 s53, s52, s20
	s_sub_i32 s5, s5, s53
	s_lshl_b32 s82, s2, 7
	s_ashr_i32 s4, s25, 31
	s_add_i32 s53, s52, 1
	s_sub_i32 s58, s5, s20
	s_cmp_ge_u32 s5, s20
	s_cselect_b32 s52, s53, s52
	s_cselect_b32 s5, s58, s5
	s_add_i32 s53, s52, 1
	s_cmp_ge_u32 s5, s20
	s_cselect_b32 s5, s53, s52
	s_xor_b32 s5, s5, s4
	s_sub_i32 s4, s5, s4
	s_not_b32 s5, s4
	s_mul_i32 s5, s20, s5
	s_add_i32 s5, s25, s5
	v_lshl_add_u64 v[50:51], v[122:123], 0, s[8:9]
	v_lshlrev_b64 v[50:51], 10, v[50:51]
	v_lshl_add_u64 v[50:51], s[48:49], 0, v[50:51]
	v_lshl_add_u64 v[50:51], v[50:51], 0, s[82:83]
	v_lshl_add_u64 v[50:51], v[50:51], 0, v[0:1]
	global_load_dwordx4 v[46:49], v[50:51], off
	global_load_dwordx4 v[42:45], v[50:51], off offset:64
	s_barrier
	s_waitcnt vmcnt(0)
	ds_write_b128 v134, v[6:9]
	ds_write_b128 v134, v[10:13] offset:53248
	ds_write_b128 v135, v[2:5]
	ds_write_b128 v136, v[22:25]
	ds_write_b128 v136, v[26:29] offset:53248
	ds_write_b128 v137, v[34:37]
	v_lshl_add_u64 v[2:3], v[122:123], 0, s[8:9]
	s_add_i32 s25, s5, 18
	v_lshlrev_b64 v[2:3], 10, v[2:3]
	s_ashr_i32 s5, s4, 3
	s_lshl_b32 s72, s25, 7
	v_lshl_add_u64 v[2:3], s[48:49], 0, v[2:3]
	s_mul_hi_i32 s52, s5, 0x900
	s_mulk_i32 s5, 0x900
	s_ashr_i32 s73, s72, 31
	v_lshl_add_u64 v[2:3], v[2:3], 0, s[82:83]
	s_add_u32 s92, s5, s72
	ds_write_b128 v245, v[14:17] offset:18432
	ds_write_b128 v246, v[18:21] offset:18432
	ds_write_b128 v247, v[30:33] offset:18432
	ds_write_b128 v248, v[38:41] offset:18432
	v_lshl_add_u64 v[2:3], v[2:3], 0, v[0:1]
	s_addc_u32 s93, s52, s73
	s_ashr_i32 s5, s4, 31
	s_mul_i32 s52, s4, 36
	s_ashr_i32 s58, s25, 31
	s_mul_hi_i32 s53, s4, 36
	s_add_u32 s52, s52, s25
	v_lshl_add_u64 v[2:3], s[92:93], 0, v[116:117]
	v_lshl_add_u64 v[14:15], s[92:93], 0, v[114:115]
	s_addc_u32 s53, s53, s58
	v_lshlrev_b64 v[2:3], 10, v[2:3]
	s_lshl_b32 s25, s4, 7
	v_lshlrev_b64 v[14:15], 10, v[14:15]
	s_lshl_b64 s[52:53], s[52:53], 14
	v_lshl_add_u64 v[2:3], s[6:7], 0, v[2:3]
	s_and_b32 s78, s25, 0x380
	s_mov_b32 s79, s83
	v_lshl_add_u64 v[14:15], s[6:7], 0, v[14:15]
	v_lshl_add_u64 v[2:3], v[2:3], 0, s[78:79]
	v_mov_b32_e32 v129, v1
	s_add_u32 s76, s62, s52
	v_lshl_add_u64 v[14:15], v[14:15], 0, s[78:79]
	v_lshl_add_u64 v[2:3], v[2:3], 0, v[128:129]
	s_addc_u32 s77, s63, s53
	v_lshl_add_u64 v[14:15], v[14:15], 0, v[128:129]
	s_waitcnt lgkmcnt(0)
	s_barrier
	global_load_dwordx4 v[6:9], v[2:3], off
	global_load_dwordx4 v[22:25], v[14:15], off
	v_lshl_add_u64 v[2:3], s[76:77], 0, v[120:121]
	s_add_u32 s74, s65, s52
	v_lshl_add_u64 v[14:15], s[76:77], 0, v[118:119]
	v_lshl_add_u64 v[2:3], v[2:3], 0, v[128:129]
	s_addc_u32 s75, s19, s53
	v_lshl_add_u64 v[14:15], v[14:15], 0, v[128:129]
	global_load_dwordx4 v[10:13], v[2:3], off
	global_load_dwordx4 v[26:29], v[14:15], off
	v_lshl_add_u64 v[2:3], s[74:75], 0, v[120:121]
	v_lshl_add_u64 v[14:15], s[74:75], 0, v[118:119]
	v_lshl_add_u64 v[2:3], v[2:3], 0, v[128:129]
	v_lshl_add_u64 v[14:15], v[14:15], 0, v[128:129]
	s_lshl_b64 s[74:75], s[4:5], 7
	global_load_dwordx4 v[2:5], v[2:3], off
	v_mov_b64_e32 v[38:39], s[54:55]
	global_load_dwordx4 v[34:37], v[14:15], off
	v_lshl_add_u64 v[14:15], s[74:75], 0, v[106:107]
	v_lshl_add_u64 v[18:19], s[74:75], 0, v[108:109]
	v_lshl_add_u64 v[30:31], s[74:75], 0, v[110:111]
	v_lshl_add_u64 v[50:51], s[74:75], 0, v[112:113]
	v_mad_u64_u32 v[16:17], s[4:5], v14, s96, v[38:39]
	v_mad_u64_u32 v[20:21], s[52:53], v18, s96, v[38:39]
	v_mad_u64_u32 v[32:33], s[52:53], v30, s96, v[38:39]
	v_mad_u64_u32 v[38:39], s[52:53], v50, s96, v[38:39]
	s_load_dwordx2 s[74:75], s[46:47], 0x60
	v_mad_i32_i24 v17, v15, s96, v17
	s_lshl_b64 s[4:5], s[72:73], 1
	v_mad_i32_i24 v21, v19, s96, v21
	v_mad_i32_i24 v33, v31, s96, v33
	v_mad_i32_i24 v39, v51, s96, v39
	v_lshl_add_u64 v[14:15], v[16:17], 0, s[4:5]
	v_lshl_add_u64 v[18:19], v[20:21], 0, s[4:5]
	v_lshl_add_u64 v[30:31], v[32:33], 0, s[4:5]
	v_lshl_add_u64 v[38:39], v[38:39], 0, s[4:5]
	s_or_b32 s4, s2, s64
	s_ashr_i32 s5, s4, 31
	s_lshl_b64 s[4:5], s[4:5], 2
	s_waitcnt lgkmcnt(0)
	s_add_u32 s78, s74, s4
	s_addc_u32 s79, s75, s5
	s_load_dword s98, s[78:79], 0x0
	s_load_dword s99, s[78:79], 0x20
	s_mov_b32 s76, 0xb2a5705f
	s_mov_b32 s77, 0x42ce8ed0
	s_mov_b32 s58, 0xc2b17218
	s_mov_b32 s25, 0x3f2aaaab
	s_mov_b32 s72, 0x7f800000
	s_mov_b32 s73, 0x33800000
	v_lshlrev_b32_e32 v40, 1, v104
	v_mov_b32_e32 v41, v1
	v_lshl_add_u64 v[14:15], v[14:15], 0, v[40:41]
	v_lshl_add_u64 v[18:19], v[18:19], 0, v[40:41]
	v_lshl_add_u64 v[30:31], v[30:31], 0, v[40:41]
	v_lshl_add_u64 v[38:39], v[38:39], 0, v[40:41]
	global_load_dwordx4 v[14:17], v[14:15], off
	v_readlane_b32 s4, v254, 38
	global_load_dwordx4 v[18:21], v[18:19], off
	v_readlane_b32 s5, v254, 39
	global_load_dwordx4 v[30:33], v[30:31], off
	v_add_u32_e32 v82, 0x4800, v230
	global_load_dwordx4 v[38:41], v[38:39], off
	s_mov_b32 s53, s64
	s_waitcnt vmcnt(10) lgkmcnt(0)
; #define LAS __attribute__((address_space(3)))
; __device__ __forceinline__ unsigned pk2(float lo, float hi) { const f32x2_t v = {lo, hi}; const bf16v2_t b = __builtin_convertvector(v, bf16v2_t); return __builtin_bit_cast(unsigned, b); }
; __device__ __forceinline__ float softplusf_(float x) { return fmaxf(x, 0.f) + log1pf(expf(-fabsf(x))); }
; __device__ __forceinline__ float log2_gamma(const Args& A, const Frame& F, int l, int dir, int h) {
;     const float x = GIN(12)[(l * 2 + dir) * NH + h];
;     return -softplusf_(-x) * 1.4426950408889634f;
; }
; __device__ __forceinline__ void ret_out_phase(const Args& A, Frame& F, int l, bool lastl, bf16_t* ARET, bf16_t* ALRU) {
;     ...
;         const float l2f = log2_gamma(A, F, l, 0, h), l2b = log2_gamma(A, F, l, 1, h);
;         bf16x8 pa[4];
;         {
;             const int i_loc = 16 * w + fr;
; #pragma unroll
;             for (int jp = 0; jp < 4; ++jp) {
;                 f32x4 c0 = (f32x4){0.f, 0.f, 0.f, 0.f}, c1 = c0;
; #pragma unroll
;                 for (int ks = 0; ks < 2; ++ks) {
;                     const bf16x8 k0 = *(const LAS bf16x8*)(ks_ + (32 * jp + fr) * 72 + 32 * ks + 8 * fq);
;                     const bf16x8 k1 = *(const LAS bf16x8*)(ks_ + (32 * jp + 16 + fr) * 72 + 32 * ks + 8 * fq);
;                     c0 = __builtin_amdgcn_mfma_f32_16x16x32_bf16(k0, qf[ks], c0, 0, 0, 0);
;                     c1 = __builtin_amdgcn_mfma_f32_16x16x32_bf16(k1, qf[ks], c1, 0, 0, 0);
;                 }
;                 float v[8];
; #pragma unroll
;                 for (int r = 0; r < 4; ++r) {
;                     const int j0 = 32 * jp + 4 * fq + r, j1 = j0 + 16;
;                     const int d0 = i_loc - j0, d1 = i_loc - j1;
;                     v[r] = c0[r] * (d0 >= 0 ? exp2f((float)d0 * l2f) : exp2f((float)(-d0) * l2b));
;                     v[4 + r] = c1[r] * (d1 >= 0 ? exp2f((float)d1 * l2f) : exp2f((float)(-d1) * l2b));
;                 }
;                 u32x4 pv; pv[0] = pk2(v[0], v[1]); pv[1] = pk2(v[2], v[3]); pv[2] = pk2(v[4], v[5]); pv[3] = pk2(v[6], v[7]);
;                 pa[jp] = __builtin_bit_cast(bf16x8, pv);
;             }
	s_mov_b32 s100, 0x3c800000
	v_mov_b32_e32 v50, s98
	v_and_b32_e32 v51, 0x7fffffff, v50
	v_mul_f32_e32 v51, 0xbfb8aa3b, v51
	v_exp_f32_e32 v51, v51
	v_mov_b32_e32 v52, 0x3e4ccccd
	v_fmaak_f32 v52, v51, v52, 0xbe800000
	v_fmaak_f32 v52, v51, v52, 0x3eaaaaab
	v_fmaak_f32 v52, v51, v52, 0xbf000000
	v_fmaak_f32 v52, v51, v52, 0x3f800000
	v_mul_f32_e32 v52, v51, v52
	v_add_f32_e32 v53, 1.0, v51
	v_log_f32_e32 v53, v53
	v_cmp_gt_f32_e64 s[74:75], s100, v51
	v_mul_f32_e32 v53, 0x3f317218, v53
	s_nop 1
	v_cndmask_b32_e64 v52, v53, v52, s[74:75]
	v_max_f32_e64 v53, -v50, 0
	v_add_f32_e32 v52, v53, v52
	v_mul_f32_e32 v66, 0xbfb8aa3b, v52
	v_mov_b32_e32 v54, s99
	v_and_b32_e32 v55, 0x7fffffff, v54
	v_mul_f32_e32 v55, 0xbfb8aa3b, v55
	v_exp_f32_e32 v55, v55
	v_mov_b32_e32 v56, 0x3e4ccccd
	v_fmaak_f32 v56, v55, v56, 0xbe800000
	v_fmaak_f32 v56, v55, v56, 0x3eaaaaab
	v_fmaak_f32 v56, v55, v56, 0xbf000000
	v_fmaak_f32 v56, v55, v56, 0x3f800000
	v_mul_f32_e32 v56, v55, v56
	v_add_f32_e32 v57, 1.0, v55
	v_log_f32_e32 v57, v57
	v_cmp_gt_f32_e64 s[74:75], s100, v55
	v_mul_f32_e32 v57, 0x3f317218, v57
	s_nop 1
	v_cndmask_b32_e64 v56, v57, v56, s[74:75]
	v_max_f32_e64 v57, -v54, 0
	v_add_f32_e32 v56, v57, v56
	v_mul_f32_e32 v67, 0xbfb8aa3b, v56
	ds_read_b128 v[50:53], v143
	ds_read_b128 v[54:57], v143 offset:2304
	s_waitcnt lgkmcnt(1)
	v_mfma_f32_16x16x32_bf16 v[50:53], v[50:53], v[46:49], 0
	ds_read_b128 v[58:61], v143 offset:64
	ds_read_b128 v[62:65], v143 offset:2368
	s_waitcnt lgkmcnt(1)
	v_mfma_f32_16x16x32_bf16 v[50:53], v[58:61], v[42:45], v[50:53]
	v_mul_f32_e32 v58, v67, v144
	v_mul_f32_e32 v59, v66, v145
	v_cndmask_b32_e64 v58, v59, v58, s[4:5]
	v_cmp_gt_f32_e64 s[74:75], s3, v58
	v_readlane_b32 s4, v254, 36
	v_mul_f32_e32 v60, v66, v147
	v_cndmask_b32_e64 v59, 0, v183, s[74:75]
	v_add_f32_e32 v58, v58, v59
	v_exp_f32_e32 v58, v58
	v_cndmask_b32_e64 v59, 0, v184, s[74:75]
	v_readlane_b32 s5, v254, 37
	v_mul_f32_e32 v61, v67, v148
	v_ldexp_f32 v58, v58, v59
	v_mul_f32_e32 v59, v67, v146
	v_cndmask_b32_e64 v59, v60, v59, s[4:5]
	v_cmp_gt_f32_e64 s[74:75], s3, v59
	v_readlane_b32 s4, v254, 40
	v_readlane_b32 s5, v254, 41
	v_cndmask_b32_e64 v60, 0, v183, s[74:75]
	v_add_f32_e32 v59, v59, v60
	v_exp_f32_e32 v59, v59
	v_cndmask_b32_e64 v60, 0, v184, s[74:75]
	v_mfma_f32_16x16x32_bf16 v[54:57], v[54:57], v[46:49], 0
	v_ldexp_f32 v60, v59, v60
	v_mul_f32_e32 v59, v66, v149
	v_cndmask_b32_e64 v59, v59, v61, s[4:5]
	v_cmp_gt_f32_e64 s[74:75], s3, v59
	v_readlane_b32 s4, v254, 42
	v_readlane_b32 s5, v254, 43
	v_cndmask_b32_e64 v61, 0, v183, s[74:75]
	v_add_f32_e32 v59, v59, v61
	v_exp_f32_e32 v59, v59
	v_cndmask_b32_e64 v61, 0, v184, s[74:75]
	s_waitcnt lgkmcnt(0)
	v_mfma_f32_16x16x32_bf16 v[54:57], v[62:65], v[42:45], v[54:57]
	v_ldexp_f32 v59, v59, v61
	v_pk_mul_f32 v[50:51], v[50:51], v[58:59]
	v_mul_f32_e32 v58, v66, v151
	v_mul_f32_e32 v59, v67, v150
	v_cndmask_b32_e64 v58, v58, v59, s[4:5]
	v_cmp_gt_f32_e64 s[74:75], s3, v58
	v_readlane_b32 s4, v254, 44
	v_readlane_b32 s5, v254, 45
	v_cndmask_b32_e64 v59, 0, v183, s[74:75]
	v_add_f32_e32 v58, v58, v59
	v_exp_f32_e32 v58, v58
	v_cndmask_b32_e64 v59, 0, v184, s[74:75]
	v_cvt_pk_bf16_f32 v50, v50, v51
	v_ldexp_f32 v61, v58, v59
	v_mul_f32_e32 v58, v66, v153
	v_mul_f32_e32 v59, v67, v152
	v_cndmask_b32_e64 v58, v58, v59, s[4:5]
	v_cmp_gt_f32_e64 s[74:75], s3, v58
	v_readlane_b32 s4, v254, 46
	v_pk_mul_f32 v[54:55], v[54:55], v[60:61]
	v_cndmask_b32_e64 v59, 0, v183, s[74:75]
	v_add_f32_e32 v58, v58, v59
	v_exp_f32_e32 v58, v58
	v_cndmask_b32_e64 v59, 0, v184, s[74:75]
	v_mul_f32_e32 v60, v67, v154
	v_readlane_b32 s5, v254, 47
	v_ldexp_f32 v58, v58, v59
	v_mul_f32_e32 v59, v66, v155
	v_cndmask_b32_e64 v59, v59, v60, s[4:5]
	v_cmp_gt_f32_e64 s[74:75], s3, v59
	v_readlane_b32 s4, v254, 48
	v_mul_f32_e32 v61, v67, v156
	v_cndmask_b32_e64 v60, 0, v183, s[74:75]
	v_add_f32_e32 v59, v59, v60
	v_exp_f32_e32 v59, v59
	v_cndmask_b32_e64 v60, 0, v184, s[74:75]
	v_readlane_b32 s5, v254, 49
	v_ldexp_f32 v60, v59, v60
	v_mul_f32_e32 v59, v66, v157
	v_cndmask_b32_e64 v59, v59, v61, s[4:5]
	v_cmp_gt_f32_e64 s[74:75], s3, v59
	v_readlane_b32 s4, v254, 50
	v_readlane_b32 s5, v254, 51
	v_cndmask_b32_e64 v61, 0, v183, s[74:75]
	v_add_f32_e32 v59, v59, v61
	v_exp_f32_e32 v59, v59
	v_cndmask_b32_e64 v61, 0, v184, s[74:75]
	v_ldexp_f32 v59, v59, v61
	v_pk_mul_f32 v[52:53], v[52:53], v[58:59]
	v_mul_f32_e32 v58, v66, v159
	v_mul_f32_e32 v59, v67, v158
	v_cndmask_b32_e64 v58, v58, v59, s[4:5]
	v_cmp_gt_f32_e64 s[74:75], s3, v58
	v_cvt_pk_bf16_f32 v51, v52, v53
	v_cvt_pk_bf16_f32 v52, v54, v55
	v_cndmask_b32_e64 v59, 0, v183, s[74:75]
	v_add_f32_e32 v58, v58, v59
	v_exp_f32_e32 v58, v58
	v_cndmask_b32_e64 v59, 0, v184, s[74:75]
	v_readlane_b32 s4, v254, 52
	v_readlane_b32 s5, v254, 53
	v_ldexp_f32 v61, v58, v59
	v_pk_mul_f32 v[56:57], v[56:57], v[60:61]
	s_nop 0
	v_cvt_pk_bf16_f32 v53, v56, v57
	ds_read_b128 v[54:57], v160
	ds_read_b128 v[58:61], v160 offset:2304
	s_waitcnt lgkmcnt(1)
	v_mfma_f32_16x16x32_bf16 v[54:57], v[54:57], v[46:49], 0
	ds_read_b128 v[62:65], v160 offset:64
	ds_read_b128 v[68:71], v160 offset:2368
	s_waitcnt lgkmcnt(1)
; #define LAS __attribute__((address_space(3)))
; __device__ __forceinline__ unsigned pk2(float lo, float hi) { const f32x2_t v = {lo, hi}; const bf16v2_t b = __builtin_convertvector(v, bf16v2_t); return __builtin_bit_cast(unsigned, b); }
; __device__ __forceinline__ void ret_out_phase(const Args& A, Frame& F, int l, bool lastl, bf16_t* ARET, bf16_t* ALRU) {
;     ...
;             for (int jp = 0; jp < 4; ++jp) {
;                 f32x4 c0 = (f32x4){0.f, 0.f, 0.f, 0.f}, c1 = c0;
; #pragma unroll
;                 for (int ks = 0; ks < 2; ++ks) {
;                     const bf16x8 k0 = *(const LAS bf16x8*)(ks_ + (32 * jp + fr) * 72 + 32 * ks + 8 * fq);
;                     const bf16x8 k1 = *(const LAS bf16x8*)(ks_ + (32 * jp + 16 + fr) * 72 + 32 * ks + 8 * fq);
;                     c0 = __builtin_amdgcn_mfma_f32_16x16x32_bf16(k0, qf[ks], c0, 0, 0, 0);
;                     c1 = __builtin_amdgcn_mfma_f32_16x16x32_bf16(k1, qf[ks], c1, 0, 0, 0);
;                 }
;                 float v[8];
; #pragma unroll
;                 for (int r = 0; r < 4; ++r) {
;                     const int j0 = 32 * jp + 4 * fq + r, j1 = j0 + 16;
;                     const int d0 = i_loc - j0, d1 = i_loc - j1;
;                     v[r] = c0[r] * (d0 >= 0 ? exp2f((float)d0 * l2f) : exp2f((float)(-d0) * l2b));
;                     v[4 + r] = c1[r] * (d1 >= 0 ? exp2f((float)d1 * l2f) : exp2f((float)(-d1) * l2b));
;                 }
;                 u32x4 pv; pv[0] = pk2(v[0], v[1]); pv[1] = pk2(v[2], v[3]); pv[2] = pk2(v[4], v[5]); pv[3] = pk2(v[6], v[7]);
;                 pa[jp] = __builtin_bit_cast(bf16x8, pv);
;             }
	v_mfma_f32_16x16x32_bf16 v[54:57], v[62:65], v[42:45], v[54:57]
	v_mul_f32_e32 v62, v66, v162
	v_mul_f32_e32 v63, v67, v161
	v_cndmask_b32_e64 v62, v62, v63, s[4:5]
	v_cmp_gt_f32_e64 s[74:75], s3, v62
	v_readlane_b32 s4, v254, 54
	v_mul_f32_e32 v64, v67, v163
	v_cndmask_b32_e64 v63, 0, v183, s[74:75]
	v_add_f32_e32 v62, v62, v63
	v_exp_f32_e32 v62, v62
	v_cndmask_b32_e64 v63, 0, v184, s[74:75]
	v_readlane_b32 s5, v254, 55
	v_mul_f32_e32 v65, v67, v165
	v_ldexp_f32 v62, v62, v63
	v_mul_f32_e32 v63, v66, v164
	v_cndmask_b32_e64 v63, v63, v64, s[4:5]
	v_cmp_gt_f32_e64 s[74:75], s3, v63
	v_readlane_b32 s4, v254, 56
	v_readlane_b32 s5, v254, 57
	v_cndmask_b32_e64 v64, 0, v183, s[74:75]
	v_add_f32_e32 v63, v63, v64
	v_exp_f32_e32 v63, v63
	v_cndmask_b32_e64 v64, 0, v184, s[74:75]
	v_mfma_f32_16x16x32_bf16 v[58:61], v[58:61], v[46:49], 0
	v_ldexp_f32 v64, v63, v64
	v_mul_f32_e32 v63, v66, v166
	v_cndmask_b32_e64 v63, v63, v65, s[4:5]
	v_cmp_gt_f32_e64 s[74:75], s3, v63
	v_readlane_b32 s4, v254, 58
	v_readlane_b32 s5, v254, 59
	v_cndmask_b32_e64 v65, 0, v183, s[74:75]
	v_add_f32_e32 v63, v63, v65
	v_exp_f32_e32 v63, v63
	v_cndmask_b32_e64 v65, 0, v184, s[74:75]
	s_waitcnt lgkmcnt(0)
	v_mfma_f32_16x16x32_bf16 v[58:61], v[68:71], v[42:45], v[58:61]
	v_ldexp_f32 v63, v63, v65
	v_pk_mul_f32 v[54:55], v[54:55], v[62:63]
	v_mul_f32_e32 v62, v66, v168
	v_mul_f32_e32 v63, v67, v167
	v_cndmask_b32_e64 v62, v62, v63, s[4:5]
	v_cmp_gt_f32_e64 s[74:75], s3, v62
	v_readlane_b32 s4, v254, 60
	v_readlane_b32 s5, v254, 61
	v_cndmask_b32_e64 v63, 0, v183, s[74:75]
	v_add_f32_e32 v62, v62, v63
	v_exp_f32_e32 v62, v62
	v_cndmask_b32_e64 v63, 0, v184, s[74:75]
	v_cvt_pk_bf16_f32 v54, v54, v55
	v_ldexp_f32 v65, v62, v63
	v_mul_f32_e32 v62, v66, v189
	v_mul_f32_e32 v63, v67, v169
	v_cndmask_b32_e64 v62, v62, v63, s[4:5]
	v_cmp_gt_f32_e64 s[74:75], s3, v62
	v_readlane_b32 s4, v254, 62
	v_pk_mul_f32 v[58:59], v[58:59], v[64:65]
	v_cndmask_b32_e64 v63, 0, v183, s[74:75]
	v_add_f32_e32 v62, v62, v63
	v_exp_f32_e32 v62, v62
	v_cndmask_b32_e64 v63, 0, v184, s[74:75]
	v_mul_f32_e32 v64, v67, v190
	v_readlane_b32 s5, v254, 63
	v_ldexp_f32 v62, v62, v63
	v_mul_f32_e32 v63, v66, v191
	v_cndmask_b32_e64 v63, v63, v64, s[4:5]
	v_cmp_gt_f32_e64 s[74:75], s3, v63
	v_readlane_b32 s4, v255, 0
	v_mul_f32_e32 v65, v67, v192
	v_cndmask_b32_e64 v64, 0, v183, s[74:75]
	v_add_f32_e32 v63, v63, v64
	v_exp_f32_e32 v63, v63
	v_cndmask_b32_e64 v64, 0, v184, s[74:75]
	v_readlane_b32 s5, v255, 1
	v_ldexp_f32 v64, v63, v64
	v_mul_f32_e32 v63, v66, v193
	v_cndmask_b32_e64 v63, v63, v65, s[4:5]
	v_cmp_gt_f32_e64 s[74:75], s3, v63
	v_readlane_b32 s4, v255, 2
	v_readlane_b32 s5, v255, 3
	v_cndmask_b32_e64 v65, 0, v183, s[74:75]
	v_add_f32_e32 v63, v63, v65
	v_exp_f32_e32 v63, v63
	v_cndmask_b32_e64 v65, 0, v184, s[74:75]
	v_ldexp_f32 v63, v63, v65
	v_pk_mul_f32 v[56:57], v[56:57], v[62:63]
	v_mul_f32_e32 v62, v66, v195
	v_mul_f32_e32 v63, v67, v194
	v_cndmask_b32_e64 v62, v62, v63, s[4:5]
	v_cmp_gt_f32_e64 s[74:75], s3, v62
	v_cvt_pk_bf16_f32 v55, v56, v57
	v_cvt_pk_bf16_f32 v56, v58, v59
	v_cndmask_b32_e64 v63, 0, v183, s[74:75]
	v_add_f32_e32 v62, v62, v63
	v_exp_f32_e32 v62, v62
	v_cndmask_b32_e64 v63, 0, v184, s[74:75]
	v_readlane_b32 s4, v255, 4
	v_readlane_b32 s5, v255, 5
	v_ldexp_f32 v65, v62, v63
	v_pk_mul_f32 v[60:61], v[60:61], v[64:65]
	s_nop 0
	v_cvt_pk_bf16_f32 v57, v60, v61
	ds_read_b128 v[58:61], v196
	ds_read_b128 v[62:65], v196 offset:2304
	s_waitcnt lgkmcnt(1)
	v_mfma_f32_16x16x32_bf16 v[58:61], v[58:61], v[46:49], 0
	ds_read_b128 v[68:71], v196 offset:64
	ds_read_b128 v[72:75], v196 offset:2368
	s_waitcnt lgkmcnt(1)
	v_mfma_f32_16x16x32_bf16 v[58:61], v[68:71], v[42:45], v[58:61]
	v_mul_f32_e32 v68, v66, v198
	v_mul_f32_e32 v69, v67, v197
	v_cndmask_b32_e64 v68, v68, v69, s[4:5]
	v_cmp_gt_f32_e64 s[74:75], s3, v68
	v_readlane_b32 s4, v255, 6
	v_mul_f32_e32 v70, v67, v199
	v_cndmask_b32_e64 v69, 0, v183, s[74:75]
	v_add_f32_e32 v68, v68, v69
	v_exp_f32_e32 v68, v68
	v_cndmask_b32_e64 v69, 0, v184, s[74:75]
	v_readlane_b32 s5, v255, 7
	v_mul_f32_e32 v71, v67, v201
	v_ldexp_f32 v68, v68, v69
	v_mul_f32_e32 v69, v66, v200
	v_cndmask_b32_e64 v69, v69, v70, s[4:5]
	v_cmp_gt_f32_e64 s[74:75], s3, v69
	v_readlane_b32 s4, v255, 8
	v_readlane_b32 s5, v255, 9
	v_cndmask_b32_e64 v70, 0, v183, s[74:75]
	v_add_f32_e32 v69, v69, v70
	v_exp_f32_e32 v69, v69
	v_cndmask_b32_e64 v70, 0, v184, s[74:75]
	v_mfma_f32_16x16x32_bf16 v[62:65], v[62:65], v[46:49], 0
	v_ldexp_f32 v70, v69, v70
	v_mul_f32_e32 v69, v66, v202
	v_cndmask_b32_e64 v69, v69, v71, s[4:5]
	v_cmp_gt_f32_e64 s[74:75], s3, v69
	v_readlane_b32 s4, v255, 10
	v_readlane_b32 s5, v255, 11
	v_cndmask_b32_e64 v71, 0, v183, s[74:75]
	v_add_f32_e32 v69, v69, v71
	v_exp_f32_e32 v69, v69
	v_cndmask_b32_e64 v71, 0, v184, s[74:75]
	s_waitcnt lgkmcnt(0)
; #define LAS __attribute__((address_space(3)))
; __device__ __forceinline__ unsigned pk2(float lo, float hi) { const f32x2_t v = {lo, hi}; const bf16v2_t b = __builtin_convertvector(v, bf16v2_t); return __builtin_bit_cast(unsigned, b); }
; __device__ __forceinline__ void ret_out_phase(const Args& A, Frame& F, int l, bool lastl, bf16_t* ARET, bf16_t* ALRU) {
;     ...
;             for (int jp = 0; jp < 4; ++jp) {
;                 f32x4 c0 = (f32x4){0.f, 0.f, 0.f, 0.f}, c1 = c0;
; #pragma unroll
;                 for (int ks = 0; ks < 2; ++ks) {
;                     const bf16x8 k0 = *(const LAS bf16x8*)(ks_ + (32 * jp + fr) * 72 + 32 * ks + 8 * fq);
;                     const bf16x8 k1 = *(const LAS bf16x8*)(ks_ + (32 * jp + 16 + fr) * 72 + 32 * ks + 8 * fq);
;                     c0 = __builtin_amdgcn_mfma_f32_16x16x32_bf16(k0, qf[ks], c0, 0, 0, 0);
;                     c1 = __builtin_amdgcn_mfma_f32_16x16x32_bf16(k1, qf[ks], c1, 0, 0, 0);
;                 }
;                 float v[8];
; #pragma unroll
;                 for (int r = 0; r < 4; ++r) {
;                     const int j0 = 32 * jp + 4 * fq + r, j1 = j0 + 16;
;                     const int d0 = i_loc - j0, d1 = i_loc - j1;
;                     v[r] = c0[r] * (d0 >= 0 ? exp2f((float)d0 * l2f) : exp2f((float)(-d0) * l2b));
;                     v[4 + r] = c1[r] * (d1 >= 0 ? exp2f((float)d1 * l2f) : exp2f((float)(-d1) * l2b));
;                 }
;                 u32x4 pv; pv[0] = pk2(v[0], v[1]); pv[1] = pk2(v[2], v[3]); pv[2] = pk2(v[4], v[5]); pv[3] = pk2(v[6], v[7]);
;                 pa[jp] = __builtin_bit_cast(bf16x8, pv);
;             }
	v_mfma_f32_16x16x32_bf16 v[62:65], v[72:75], v[42:45], v[62:65]
	v_ldexp_f32 v69, v69, v71
	v_pk_mul_f32 v[58:59], v[58:59], v[68:69]
	v_mul_f32_e32 v68, v66, v204
	v_mul_f32_e32 v69, v67, v203
	v_cndmask_b32_e64 v68, v68, v69, s[4:5]
	v_cmp_gt_f32_e64 s[74:75], s3, v68
	v_readlane_b32 s4, v255, 12
	v_readlane_b32 s5, v255, 13
	v_cndmask_b32_e64 v69, 0, v183, s[74:75]
	v_add_f32_e32 v68, v68, v69
	v_exp_f32_e32 v68, v68
	v_cndmask_b32_e64 v69, 0, v184, s[74:75]
	v_cvt_pk_bf16_f32 v58, v58, v59
	v_ldexp_f32 v71, v68, v69
	v_mul_f32_e32 v68, v66, v206
	v_mul_f32_e32 v69, v67, v205
	v_cndmask_b32_e64 v68, v68, v69, s[4:5]
	v_cmp_gt_f32_e64 s[74:75], s3, v68
	v_readlane_b32 s4, v255, 14
	v_pk_mul_f32 v[62:63], v[62:63], v[70:71]
	v_cndmask_b32_e64 v69, 0, v183, s[74:75]
	v_add_f32_e32 v68, v68, v69
	v_exp_f32_e32 v68, v68
	v_cndmask_b32_e64 v69, 0, v184, s[74:75]
	v_mul_f32_e32 v70, v67, v207
	v_readlane_b32 s5, v255, 15
	v_ldexp_f32 v68, v68, v69
	v_mul_f32_e32 v69, v66, v208
	v_cndmask_b32_e64 v69, v69, v70, s[4:5]
	v_cmp_gt_f32_e64 s[74:75], s3, v69
	v_readlane_b32 s4, v255, 16
	v_mul_f32_e32 v71, v67, v209
	v_cndmask_b32_e64 v70, 0, v183, s[74:75]
	v_add_f32_e32 v69, v69, v70
	v_exp_f32_e32 v69, v69
	v_cndmask_b32_e64 v70, 0, v184, s[74:75]
	v_readlane_b32 s5, v255, 17
	v_ldexp_f32 v70, v69, v70
	v_mul_f32_e32 v69, v66, v210
	v_cndmask_b32_e64 v69, v69, v71, s[4:5]
	v_cmp_gt_f32_e64 s[74:75], s3, v69
	v_readlane_b32 s4, v255, 18
	v_readlane_b32 s5, v255, 19
	v_cndmask_b32_e64 v71, 0, v183, s[74:75]
	v_add_f32_e32 v69, v69, v71
	v_exp_f32_e32 v69, v69
	v_cndmask_b32_e64 v71, 0, v184, s[74:75]
	v_ldexp_f32 v69, v69, v71
	v_pk_mul_f32 v[60:61], v[60:61], v[68:69]
	v_mul_f32_e32 v68, v66, v212
	v_mul_f32_e32 v69, v67, v211
	v_cndmask_b32_e64 v68, v68, v69, s[4:5]
	v_cmp_gt_f32_e64 s[74:75], s3, v68
	v_cvt_pk_bf16_f32 v59, v60, v61
	v_cvt_pk_bf16_f32 v60, v62, v63
	v_cndmask_b32_e64 v69, 0, v183, s[74:75]
	v_add_f32_e32 v68, v68, v69
	v_exp_f32_e32 v68, v68
	v_cndmask_b32_e64 v69, 0, v184, s[74:75]
	v_readlane_b32 s4, v255, 20
	v_readlane_b32 s5, v255, 21
	v_ldexp_f32 v71, v68, v69
	v_pk_mul_f32 v[64:65], v[64:65], v[70:71]
	s_nop 0
	v_cvt_pk_bf16_f32 v61, v64, v65
	ds_read_b128 v[62:65], v213
	ds_read_b128 v[68:71], v213 offset:2304
	s_waitcnt lgkmcnt(1)
	v_mfma_f32_16x16x32_bf16 v[62:65], v[62:65], v[46:49], 0
	ds_read_b128 v[72:75], v213 offset:64
	ds_read_b128 v[76:79], v213 offset:2368
	s_waitcnt lgkmcnt(1)
	v_mfma_f32_16x16x32_bf16 v[62:65], v[72:75], v[42:45], v[62:65]
	v_mul_f32_e32 v72, v66, v215
	v_mul_f32_e32 v73, v67, v214
	v_cndmask_b32_e64 v72, v72, v73, s[4:5]
	v_cmp_gt_f32_e64 s[74:75], s3, v72
	v_readlane_b32 s4, v255, 22
	v_mul_f32_e32 v74, v67, v216
	v_cndmask_b32_e64 v73, 0, v183, s[74:75]
	v_add_f32_e32 v72, v72, v73
	v_exp_f32_e32 v72, v72
	v_cndmask_b32_e64 v73, 0, v184, s[74:75]
	v_readlane_b32 s5, v255, 23
	v_mul_f32_e32 v75, v67, v218
	v_ldexp_f32 v72, v72, v73
	v_mul_f32_e32 v73, v66, v217
	v_cndmask_b32_e64 v73, v73, v74, s[4:5]
	v_cmp_gt_f32_e64 s[74:75], s3, v73
	v_readlane_b32 s4, v255, 24
	v_readlane_b32 s5, v255, 25
	v_cndmask_b32_e64 v74, 0, v183, s[74:75]
	v_add_f32_e32 v73, v73, v74
	v_exp_f32_e32 v73, v73
	v_cndmask_b32_e64 v74, 0, v184, s[74:75]
	v_mfma_f32_16x16x32_bf16 v[68:71], v[68:71], v[46:49], 0
	v_ldexp_f32 v74, v73, v74
	v_mul_f32_e32 v73, v66, v219
	v_cndmask_b32_e64 v73, v73, v75, s[4:5]
	v_cmp_gt_f32_e64 s[74:75], s3, v73
	v_readlane_b32 s4, v255, 26
	v_readlane_b32 s5, v255, 27
	v_cndmask_b32_e64 v75, 0, v183, s[74:75]
	v_add_f32_e32 v73, v73, v75
	v_exp_f32_e32 v73, v73
	v_cndmask_b32_e64 v75, 0, v184, s[74:75]
	s_waitcnt lgkmcnt(0)
	v_mfma_f32_16x16x32_bf16 v[68:71], v[76:79], v[42:45], v[68:71]
	v_ldexp_f32 v73, v73, v75
	v_pk_mul_f32 v[62:63], v[62:63], v[72:73]
	v_mul_f32_e32 v72, v66, v221
	v_mul_f32_e32 v73, v67, v220
	v_cndmask_b32_e64 v72, v72, v73, s[4:5]
	v_cmp_gt_f32_e64 s[74:75], s3, v72
	v_readlane_b32 s4, v255, 28
	v_readlane_b32 s5, v255, 29
	v_cndmask_b32_e64 v73, 0, v183, s[74:75]
	v_add_f32_e32 v72, v72, v73
	v_exp_f32_e32 v72, v72
	v_cndmask_b32_e64 v73, 0, v184, s[74:75]
	v_cvt_pk_bf16_f32 v62, v62, v63
	v_ldexp_f32 v75, v72, v73
	v_mul_f32_e32 v72, v66, v223
	v_mul_f32_e32 v73, v67, v222
	v_cndmask_b32_e64 v72, v72, v73, s[4:5]
	v_cmp_gt_f32_e64 s[74:75], s3, v72
	v_pk_mul_f32 v[68:69], v[68:69], v[74:75]
	v_mul_f32_e32 v74, v67, v224
	v_cndmask_b32_e64 v73, 0, v183, s[74:75]
	v_add_f32_e32 v72, v72, v73
	v_exp_f32_e32 v72, v72
	v_cndmask_b32_e64 v73, 0, v184, s[74:75]
	v_mul_f32_e32 v75, v67, v226
	v_ldexp_f32 v72, v72, v73
	v_mul_f32_e32 v73, v66, v225
	v_cndmask_b32_e64 v73, v73, v74, s[66:67]
	v_cmp_gt_f32_e64 s[74:75], s3, v73
	s_nop 1
	v_cndmask_b32_e64 v74, 0, v183, s[74:75]
	v_add_f32_e32 v73, v73, v74
	v_exp_f32_e32 v73, v73
	v_cndmask_b32_e64 v74, 0, v184, s[74:75]
	v_ldexp_f32 v74, v73, v74
	v_mul_f32_e32 v73, v66, v227
	v_cndmask_b32_e64 v73, v73, v75, s[68:69]
	v_cmp_gt_f32_e64 s[74:75], s3, v73
	s_nop 1
	v_cndmask_b32_e64 v75, 0, v183, s[74:75]
	v_add_f32_e32 v73, v73, v75
	v_exp_f32_e32 v73, v73
	v_cndmask_b32_e64 v75, 0, v184, s[74:75]
	v_ldexp_f32 v73, v73, v75
	v_pk_mul_f32 v[64:65], v[64:65], v[72:73]
	v_mul_f32_e32 v72, v66, v229
	v_mul_f32_e32 v73, v67, v228
	v_cndmask_b32_e64 v72, v72, v73, s[70:71]
	v_cmp_gt_f32_e64 s[74:75], s3, v72
	v_cvt_pk_bf16_f32 v63, v64, v65
	v_cvt_pk_bf16_f32 v64, v68, v69
	v_cndmask_b32_e64 v73, 0, v183, s[74:75]
	v_mul_f32_e32 v68, v66, v103
	v_add_f32_e32 v72, v72, v73
	v_cndmask_b32_e64 v73, 0, v184, s[74:75]
	v_cmp_gt_f32_e64 s[74:75], s3, v68
	v_exp_f32_e32 v72, v72
	v_and_b32_e32 v69, 0xffff0000, v46
; #define LAS __attribute__((address_space(3)))
; __device__ __forceinline__ void ret_out_phase(const Args& A, Frame& F, int l, bool lastl, bf16_t* ARET, bf16_t* ALRU) {
;     ...
;         bf16x8 qF[2], qB[2];
;         {
;             const int il = 16 * w + fr;
;             const float sF = exp2f((float)(il + 1) * l2f), sB = exp2f((float)(128 - il) * l2b);
; #pragma unroll
;             for (int ks = 0; ks < 2; ++ks) { qF[ks] = scale1(qf[ks], sF); qB[ks] = scale1(qf[ks], sB); }
;         }
;         f32x4 O[8];
; #pragma unroll
;         for (int dvt = 0; dvt < 8; ++dvt) {
;             f32x4 o = (f32x4){0.f, 0.f, 0.f, 0.f};
; #pragma unroll
;             for (int jp = 0; jp < 4; ++jp) {
;                 const u32x2 lo = *(const LAS u32x2*)(vts + (16 * dvt + fr) * 136 + 32 * jp + 4 * fq);
;                 const u32x2 hi = *(const LAS u32x2*)(vts + (16 * dvt + fr) * 136 + 32 * jp + 16 + 4 * fq);
;                 u32x4 bv; bv[0] = lo.x; bv[1] = lo.y; bv[2] = hi.x; bv[3] = hi.y;
;                 o = __builtin_amdgcn_mfma_f32_16x16x32_bf16(pa[jp], __builtin_bit_cast(bf16x8, bv), o, 0, 0, 0);
;             }
; #pragma unroll
;             for (int ks = 0; ks < 2; ++ks) {
;                 const bf16x8 sf = *(const LAS bf16x8*)(sfs + (16 * dvt + fr) * 72 + 32 * ks + 8 * fq);
;                 const bf16x8 sb = *(const LAS bf16x8*)(sbs + (16 * dvt + fr) * 72 + 32 * ks + 8 * fq);
;                 o = __builtin_amdgcn_mfma_f32_16x16x32_bf16(qF[ks], sf, o, 0, 0, 0);
;                 o = __builtin_amdgcn_mfma_f32_16x16x32_bf16(qB[ks], sb, o, 0, 0, 0);
;             }
;             O[dvt] = o;
;             __builtin_amdgcn_sched_barrier(0);
;         }
	v_cndmask_b32_e64 v68, 0, v183, s[74:75]
	v_fmac_f32_e32 v68, v66, v103
	v_exp_f32_e32 v66, v68
	v_ldexp_f32 v75, v72, v73
	v_cndmask_b32_e64 v68, 0, v184, s[74:75]
	v_pk_mul_f32 v[70:71], v[70:71], v[74:75]
	v_ldexp_f32 v74, v66, v68
	v_mul_f32_e32 v66, v67, v105
	v_cmp_gt_f32_e64 s[74:75], s3, v66
	v_lshlrev_b32_e32 v68, 16, v46
	v_cvt_pk_bf16_f32 v65, v70, v71
	v_cndmask_b32_e64 v66, 0, v183, s[74:75]
	v_fmac_f32_e32 v66, v67, v105
	v_exp_f32_e32 v66, v66
	v_cndmask_b32_e64 v67, 0, v184, s[74:75]
	v_ldexp_f32 v76, v66, v67
	v_pk_mul_f32 v[66:67], v[74:75], v[68:69] op_sel_hi:[0,1]
	v_pk_mul_f32 v[68:69], v[76:77], v[68:69] op_sel_hi:[0,1]
	v_cvt_pk_bf16_f32 v46, v68, v69
	v_lshlrev_b32_e32 v68, 16, v47
	v_and_b32_e32 v69, 0xffff0000, v47
	v_pk_mul_f32 v[70:71], v[74:75], v[68:69] op_sel_hi:[0,1]
	v_cvt_pk_bf16_f32 v66, v66, v67
	v_cvt_pk_bf16_f32 v67, v70, v71
	v_pk_mul_f32 v[68:69], v[76:77], v[68:69] op_sel_hi:[0,1]
	v_lshlrev_b32_e32 v70, 16, v48
	v_and_b32_e32 v71, 0xffff0000, v48
	v_cvt_pk_bf16_f32 v47, v68, v69
	v_pk_mul_f32 v[68:69], v[74:75], v[70:71] op_sel_hi:[0,1]
	v_pk_mul_f32 v[70:71], v[76:77], v[70:71] op_sel_hi:[0,1]
	v_cvt_pk_bf16_f32 v48, v70, v71
	v_lshlrev_b32_e32 v70, 16, v49
	v_and_b32_e32 v71, 0xffff0000, v49
	v_pk_mul_f32 v[72:73], v[74:75], v[70:71] op_sel_hi:[0,1]
	v_cvt_pk_bf16_f32 v68, v68, v69
	v_cvt_pk_bf16_f32 v69, v72, v73
	v_pk_mul_f32 v[70:71], v[76:77], v[70:71] op_sel_hi:[0,1]
	v_lshlrev_b32_e32 v72, 16, v42
	v_and_b32_e32 v73, 0xffff0000, v42
	v_cvt_pk_bf16_f32 v49, v70, v71
	v_pk_mul_f32 v[70:71], v[74:75], v[72:73] op_sel_hi:[0,1]
	v_pk_mul_f32 v[72:73], v[76:77], v[72:73] op_sel_hi:[0,1]
	v_cvt_pk_bf16_f32 v42, v72, v73
	v_lshlrev_b32_e32 v72, 16, v43
	v_and_b32_e32 v73, 0xffff0000, v43
	v_pk_mul_f32 v[78:79], v[74:75], v[72:73] op_sel_hi:[0,1]
	v_cvt_pk_bf16_f32 v70, v70, v71
	v_cvt_pk_bf16_f32 v71, v78, v79
	v_pk_mul_f32 v[72:73], v[76:77], v[72:73] op_sel_hi:[0,1]
	v_lshlrev_b32_e32 v78, 16, v44
	v_and_b32_e32 v79, 0xffff0000, v44
	v_cvt_pk_bf16_f32 v43, v72, v73
	v_pk_mul_f32 v[72:73], v[74:75], v[78:79] op_sel_hi:[0,1]
	v_pk_mul_f32 v[78:79], v[76:77], v[78:79] op_sel_hi:[0,1]
	v_cvt_pk_bf16_f32 v44, v78, v79
	v_lshlrev_b32_e32 v78, 16, v45
	v_and_b32_e32 v79, 0xffff0000, v45
	v_pk_mul_f32 v[74:75], v[74:75], v[78:79] op_sel_hi:[0,1]
	v_cvt_pk_bf16_f32 v72, v72, v73
	v_cvt_pk_bf16_f32 v73, v74, v75
	v_pk_mul_f32 v[74:75], v[76:77], v[78:79] op_sel_hi:[0,1]
	v_cvt_pk_bf16_f32 v45, v74, v75
	ds_read2_b64 v[74:77], v82 offset1:4
	ds_read2_b64 v[78:81], v82 offset0:8 offset1:12
	s_waitcnt lgkmcnt(1)
	v_mfma_f32_16x16x32_bf16 v[74:77], v[50:53], v[74:77], 0
	s_waitcnt lgkmcnt(0)
	v_mfma_f32_16x16x32_bf16 v[74:77], v[54:57], v[78:81], v[74:77]
	ds_read2_b64 v[78:81], v82 offset0:16 offset1:20
	s_waitcnt lgkmcnt(0)
	v_mfma_f32_16x16x32_bf16 v[74:77], v[58:61], v[78:81], v[74:77]
	ds_read2_b64 v[78:81], v82 offset0:24 offset1:28
	s_waitcnt lgkmcnt(0)
	v_mfma_f32_16x16x32_bf16 v[74:77], v[62:65], v[78:81], v[74:77]
	ds_read_b128 v[78:81], v231 offset:53248
	ds_read_b128 v[82:85], v232
	s_waitcnt lgkmcnt(1)
	v_mfma_f32_16x16x32_bf16 v[74:77], v[66:69], v[78:81], v[74:77]
	s_waitcnt lgkmcnt(0)
	v_mfma_f32_16x16x32_bf16 v[74:77], v[46:49], v[82:85], v[74:77]
	ds_read_b128 v[78:81], v231 offset:53312
	ds_read_b128 v[82:85], v232 offset:64
	s_waitcnt lgkmcnt(1)
	v_mfma_f32_16x16x32_bf16 v[74:77], v[70:73], v[78:81], v[74:77]
	s_waitcnt lgkmcnt(0)
	v_mfma_f32_16x16x32_bf16 v[74:77], v[42:45], v[82:85], v[74:77]
	v_add_u32_e32 v78, 0x1100, v230
	v_add_u32_e32 v86, 0x4800, v78
	ds_read2_b64 v[78:81], v86 offset1:4
	ds_read2_b64 v[82:85], v86 offset0:8 offset1:12
	s_waitcnt lgkmcnt(1)
	v_mfma_f32_16x16x32_bf16 v[78:81], v[50:53], v[78:81], 0
	s_waitcnt lgkmcnt(0)
	v_mfma_f32_16x16x32_bf16 v[78:81], v[54:57], v[82:85], v[78:81]
	ds_read2_b64 v[82:85], v86 offset0:16 offset1:20
	s_waitcnt lgkmcnt(0)
	v_mfma_f32_16x16x32_bf16 v[78:81], v[58:61], v[82:85], v[78:81]
	ds_read2_b64 v[82:85], v86 offset0:24 offset1:28
	s_waitcnt lgkmcnt(0)
	v_mfma_f32_16x16x32_bf16 v[78:81], v[62:65], v[82:85], v[78:81]
	ds_read_b128 v[82:85], v231 offset:55552
	s_waitcnt lgkmcnt(0)
	v_mfma_f32_16x16x32_bf16 v[78:81], v[66:69], v[82:85], v[78:81]
	ds_read_b128 v[82:85], v233
	s_waitcnt lgkmcnt(0)
	v_mfma_f32_16x16x32_bf16 v[78:81], v[46:49], v[82:85], v[78:81]
	ds_read_b128 v[82:85], v231 offset:55616
	s_waitcnt lgkmcnt(0)
	v_mfma_f32_16x16x32_bf16 v[78:81], v[70:73], v[82:85], v[78:81]
	ds_read_b128 v[82:85], v233 offset:64
	s_waitcnt lgkmcnt(0)
	v_mfma_f32_16x16x32_bf16 v[78:81], v[42:45], v[82:85], v[78:81]
	v_add_u32_e32 v82, 0x2200, v230
	v_add_u32_e32 v90, 0x4800, v82
	ds_read2_b64 v[82:85], v90 offset1:4
	ds_read2_b64 v[86:89], v90 offset0:8 offset1:12
	s_waitcnt lgkmcnt(1)
	v_mfma_f32_16x16x32_bf16 v[82:85], v[50:53], v[82:85], 0
	s_waitcnt lgkmcnt(0)
	v_mfma_f32_16x16x32_bf16 v[82:85], v[54:57], v[86:89], v[82:85]
	ds_read2_b64 v[86:89], v90 offset0:16 offset1:20
	s_waitcnt lgkmcnt(0)
	v_mfma_f32_16x16x32_bf16 v[82:85], v[58:61], v[86:89], v[82:85]
	ds_read2_b64 v[86:89], v90 offset0:24 offset1:28
	s_waitcnt lgkmcnt(0)
	v_mfma_f32_16x16x32_bf16 v[82:85], v[62:65], v[86:89], v[82:85]
	ds_read_b128 v[86:89], v231 offset:57856
	s_waitcnt lgkmcnt(0)
	v_mfma_f32_16x16x32_bf16 v[82:85], v[66:69], v[86:89], v[82:85]
	ds_read_b128 v[86:89], v234
	s_waitcnt lgkmcnt(0)
	v_mfma_f32_16x16x32_bf16 v[82:85], v[46:49], v[86:89], v[82:85]
	ds_read_b128 v[86:89], v231 offset:57920
	s_waitcnt lgkmcnt(0)
	v_mfma_f32_16x16x32_bf16 v[82:85], v[70:73], v[86:89], v[82:85]
	ds_read_b128 v[86:89], v234 offset:64
	s_waitcnt lgkmcnt(0)
; #define LAS __attribute__((address_space(3)))
; __device__ __forceinline__ void ret_out_phase(const Args& A, Frame& F, int l, bool lastl, bf16_t* ARET, bf16_t* ALRU) {
;     ...
;         f32x4 O[8];
; #pragma unroll
;         for (int dvt = 0; dvt < 8; ++dvt) {
;             f32x4 o = (f32x4){0.f, 0.f, 0.f, 0.f};
; #pragma unroll
;             for (int jp = 0; jp < 4; ++jp) {
;                 const u32x2 lo = *(const LAS u32x2*)(vts + (16 * dvt + fr) * 136 + 32 * jp + 4 * fq);
;                 const u32x2 hi = *(const LAS u32x2*)(vts + (16 * dvt + fr) * 136 + 32 * jp + 16 + 4 * fq);
;                 u32x4 bv; bv[0] = lo.x; bv[1] = lo.y; bv[2] = hi.x; bv[3] = hi.y;
;                 o = __builtin_amdgcn_mfma_f32_16x16x32_bf16(pa[jp], __builtin_bit_cast(bf16x8, bv), o, 0, 0, 0);
;             }
; #pragma unroll
;             for (int ks = 0; ks < 2; ++ks) {
;                 const bf16x8 sf = *(const LAS bf16x8*)(sfs + (16 * dvt + fr) * 72 + 32 * ks + 8 * fq);
;                 const bf16x8 sb = *(const LAS bf16x8*)(sbs + (16 * dvt + fr) * 72 + 32 * ks + 8 * fq);
;                 o = __builtin_amdgcn_mfma_f32_16x16x32_bf16(qF[ks], sf, o, 0, 0, 0);
;                 o = __builtin_amdgcn_mfma_f32_16x16x32_bf16(qB[ks], sb, o, 0, 0, 0);
;             }
;             O[dvt] = o;
;             __builtin_amdgcn_sched_barrier(0);
;         }
	v_mfma_f32_16x16x32_bf16 v[82:85], v[42:45], v[86:89], v[82:85]
	v_add_u32_e32 v86, 0x3300, v230
	v_add_u32_e32 v94, 0x4800, v86
	ds_read2_b64 v[86:89], v94 offset1:4
	ds_read2_b64 v[90:93], v94 offset0:8 offset1:12
	s_waitcnt lgkmcnt(1)
	v_mfma_f32_16x16x32_bf16 v[86:89], v[50:53], v[86:89], 0
	s_waitcnt lgkmcnt(0)
	v_mfma_f32_16x16x32_bf16 v[86:89], v[54:57], v[90:93], v[86:89]
	ds_read2_b64 v[90:93], v94 offset0:16 offset1:20
	s_waitcnt lgkmcnt(0)
	v_mfma_f32_16x16x32_bf16 v[86:89], v[58:61], v[90:93], v[86:89]
	ds_read2_b64 v[90:93], v94 offset0:24 offset1:28
	s_waitcnt lgkmcnt(0)
	v_mfma_f32_16x16x32_bf16 v[86:89], v[62:65], v[90:93], v[86:89]
	ds_read_b128 v[90:93], v160 offset:55552
	s_waitcnt lgkmcnt(0)
	v_mfma_f32_16x16x32_bf16 v[86:89], v[66:69], v[90:93], v[86:89]
	ds_read_b128 v[90:93], v235
	s_waitcnt lgkmcnt(0)
	v_mfma_f32_16x16x32_bf16 v[86:89], v[46:49], v[90:93], v[86:89]
	ds_read_b128 v[90:93], v160 offset:55616
	s_waitcnt lgkmcnt(0)
	v_mfma_f32_16x16x32_bf16 v[86:89], v[70:73], v[90:93], v[86:89]
	ds_read_b128 v[90:93], v235 offset:64
	s_waitcnt lgkmcnt(0)
	v_mfma_f32_16x16x32_bf16 v[86:89], v[42:45], v[90:93], v[86:89]
	v_add_u32_e32 v90, 0x4400, v230
	v_add_u32_e32 v98, 0x4800, v90
	ds_read2_b64 v[90:93], v98 offset1:4
	ds_read2_b64 v[94:97], v98 offset0:8 offset1:12
	s_waitcnt lgkmcnt(1)
	v_mfma_f32_16x16x32_bf16 v[90:93], v[50:53], v[90:93], 0
	s_waitcnt lgkmcnt(0)
	v_mfma_f32_16x16x32_bf16 v[90:93], v[54:57], v[94:97], v[90:93]
	ds_read2_b64 v[94:97], v98 offset0:16 offset1:20
	s_waitcnt lgkmcnt(0)
	v_mfma_f32_16x16x32_bf16 v[90:93], v[58:61], v[94:97], v[90:93]
	ds_read2_b64 v[94:97], v98 offset0:24 offset1:28
	s_waitcnt lgkmcnt(0)
	v_mfma_f32_16x16x32_bf16 v[90:93], v[62:65], v[94:97], v[90:93]
	ds_read_b128 v[94:97], v236 offset:53248
	s_waitcnt lgkmcnt(0)
	v_mfma_f32_16x16x32_bf16 v[90:93], v[66:69], v[94:97], v[90:93]
	ds_read_b128 v[94:97], v237
	s_waitcnt lgkmcnt(0)
	v_mfma_f32_16x16x32_bf16 v[90:93], v[46:49], v[94:97], v[90:93]
	ds_read_b128 v[94:97], v236 offset:53312
	s_waitcnt lgkmcnt(0)
	v_mfma_f32_16x16x32_bf16 v[90:93], v[70:73], v[94:97], v[90:93]
	ds_read_b128 v[94:97], v237 offset:64
	s_waitcnt lgkmcnt(0)
	v_mfma_f32_16x16x32_bf16 v[90:93], v[42:45], v[94:97], v[90:93]
	v_add_u32_e32 v94, 0x5500, v230
	v_add_u32_e32 v129, 0x4800, v94
	ds_read2_b64 v[94:97], v129 offset1:4
	ds_read2_b64 v[98:101], v129 offset0:8 offset1:12
	s_waitcnt lgkmcnt(1)
	v_mfma_f32_16x16x32_bf16 v[94:97], v[50:53], v[94:97], 0
	s_waitcnt lgkmcnt(0)
	v_mfma_f32_16x16x32_bf16 v[94:97], v[54:57], v[98:101], v[94:97]
	ds_read2_b64 v[98:101], v129 offset0:16 offset1:20
	s_waitcnt lgkmcnt(0)
	v_mfma_f32_16x16x32_bf16 v[94:97], v[58:61], v[98:101], v[94:97]
	ds_read2_b64 v[98:101], v129 offset0:24 offset1:28
	s_waitcnt lgkmcnt(0)
	v_mfma_f32_16x16x32_bf16 v[94:97], v[62:65], v[98:101], v[94:97]
	ds_read_b128 v[98:101], v238 offset:53248
	s_waitcnt lgkmcnt(0)
	v_mfma_f32_16x16x32_bf16 v[94:97], v[66:69], v[98:101], v[94:97]
	ds_read_b128 v[98:101], v239
	s_waitcnt lgkmcnt(0)
	v_mfma_f32_16x16x32_bf16 v[94:97], v[46:49], v[98:101], v[94:97]
	ds_read_b128 v[98:101], v238 offset:53312
	s_waitcnt lgkmcnt(0)
	v_mfma_f32_16x16x32_bf16 v[94:97], v[70:73], v[98:101], v[94:97]
	ds_read_b128 v[98:101], v239 offset:64
	s_waitcnt lgkmcnt(0)
	v_mfma_f32_16x16x32_bf16 v[94:97], v[42:45], v[98:101], v[94:97]
	v_add_u32_e32 v98, 0x6600, v230
	v_add_u32_e32 v129, 0x4800, v98
	ds_read2_b64 v[98:101], v129 offset1:4
	ds_read2_b64 v[250:253], v129 offset0:8 offset1:12
	s_waitcnt lgkmcnt(1)
	v_mfma_f32_16x16x32_bf16 v[98:101], v[50:53], v[98:101], 0
	s_waitcnt lgkmcnt(0)
	v_mfma_f32_16x16x32_bf16 v[98:101], v[54:57], v[250:253], v[98:101]
	ds_read2_b64 v[250:253], v129 offset0:16 offset1:20
	s_waitcnt lgkmcnt(0)
	v_mfma_f32_16x16x32_bf16 v[98:101], v[58:61], v[250:253], v[98:101]
	ds_read2_b64 v[250:253], v129 offset0:24 offset1:28
	s_waitcnt lgkmcnt(0)
	v_mfma_f32_16x16x32_bf16 v[98:101], v[62:65], v[250:253], v[98:101]
	ds_read_b128 v[250:253], v240 offset:53248
	s_waitcnt lgkmcnt(0)
	v_mfma_f32_16x16x32_bf16 v[98:101], v[66:69], v[250:253], v[98:101]
	ds_read_b128 v[250:253], v241
	s_waitcnt lgkmcnt(0)
	v_mfma_f32_16x16x32_bf16 v[98:101], v[46:49], v[250:253], v[98:101]
	ds_read_b128 v[250:253], v240 offset:53312
	s_waitcnt lgkmcnt(0)
	v_mfma_f32_16x16x32_bf16 v[98:101], v[70:73], v[250:253], v[98:101]
	ds_read_b128 v[250:253], v241 offset:64
	s_waitcnt lgkmcnt(0)
	v_mfma_f32_16x16x32_bf16 v[98:101], v[42:45], v[250:253], v[98:101]
	v_add_u32_e32 v129, 0x4800, v242
	ds_read2_b64 v[250:253], v129 offset1:4
	s_waitcnt lgkmcnt(0)
	v_mfma_f32_16x16x32_bf16 v[50:53], v[50:53], v[250:253], 0
	ds_read2_b64 v[250:253], v129 offset0:8 offset1:12
	s_waitcnt lgkmcnt(0)
	v_mfma_f32_16x16x32_bf16 v[50:53], v[54:57], v[250:253], v[50:53]
	ds_read2_b64 v[54:57], v129 offset0:16 offset1:20
	s_waitcnt lgkmcnt(0)
	v_mfma_f32_16x16x32_bf16 v[50:53], v[58:61], v[54:57], v[50:53]
	ds_read2_b64 v[54:57], v129 offset0:24 offset1:28
	s_waitcnt lgkmcnt(0)
	v_mfma_f32_16x16x32_bf16 v[50:53], v[62:65], v[54:57], v[50:53]
	ds_read_b128 v[54:57], v243 offset:53248
	ds_read_b128 v[58:61], v243 offset:53312
	s_waitcnt lgkmcnt(1)
	v_mfma_f32_16x16x32_bf16 v[50:53], v[66:69], v[54:57], v[50:53]
	ds_read_b128 v[54:57], v244
	ds_read_b128 v[62:65], v244 offset:64
	s_waitcnt lgkmcnt(1)
	v_mfma_f32_16x16x32_bf16 v[46:49], v[46:49], v[54:57], v[50:53]
	v_mfma_f32_16x16x32_bf16 v[46:49], v[70:73], v[58:61], v[46:49]
	s_waitcnt lgkmcnt(0)
; __device__ __forceinline__ bf16_t f2bf(float f) { return (bf16_t)(pk2(f, 0.f) & 0xffffu); }
; __device__ __forceinline__ float sum16(float v) {
; #pragma unroll
;     for (int o = 1; o < 16; o <<= 1) v += __shfl_xor(v, o);
;     return v;
; }
; __device__ __forceinline__ void ret_out_phase(const Args& A, Frame& F, int l, bool lastl, bf16_t* ARET, bf16_t* ALRU) {
;     ...
; #pragma unroll
;         for (int r = 0; r < 4; ++r) {
;             float sm = 0.f;
; #pragma unroll
;             for (int dvt = 0; dvt < 8; ++dvt) sm += O[dvt][r];
;             const float mu = sum16(sm) * (1.f / DV);
;             float q2 = 0.f;
; #pragma unroll
;             for (int dvt = 0; dvt < 8; ++dvt) { const float dd = O[dvt][r] - mu; q2 += dd * dd; }
;             const float rstd = rsqrtf(sum16(q2) * (1.f / DV) + EPS);
; #pragma unroll
;             for (int dvt = 0; dvt < 8; ++dvt) os[(16 * w + 4 * fq + r) * 136 + 16 * dvt + fr] = f2bf((O[dvt][r] - mu) * rstd);
;         }
	v_mfma_f32_16x16x32_bf16 v[42:45], v[42:45], v[62:65], v[46:49]
	s_nop 5
	v_add_f32_e64 v46, v74, 0
	v_add_f32_e64 v47, v75, 0
	v_mov_b32_e32 v50, v86
	v_pk_add_f32 v[46:47], v[46:47], v[78:79]
	v_mov_b32_e32 v51, v82
	v_pk_add_f32 v[46:47], v[46:47], v[82:83]
	v_mov_b32_e32 v82, v87
	v_pk_add_f32 v[46:47], v[46:47], v[86:87]
	v_mov_b32_e32 v52, v94
	v_pk_add_f32 v[46:47], v[46:47], v[90:91]
	v_mov_b32_e32 v53, v90
	v_pk_add_f32 v[46:47], v[46:47], v[94:95]
	v_mov_b32_e32 v90, v95
	v_pk_add_f32 v[46:47], v[46:47], v[98:99]
	v_mov_b32_e32 v54, v42
	v_pk_add_f32 v[46:47], v[46:47], v[42:43]
	v_mov_b32_e32 v55, v98
	v_mov_b32_e32 v98, v43
	s_mov_b32 s2, 0x358637bd
	s_add_i32 vcc_hi, vcc_hi, s34
	s_waitcnt lgkmcnt(0)
	s_nop 1
	v_add_f32_dpp v46, v46, v46 quad_perm:[1,0,3,2] row_mask:0xf bank_mask:0xf
	v_add_f32_dpp v47, v47, v47 quad_perm:[1,0,3,2] row_mask:0xf bank_mask:0xf
	s_add_i32 s61, s61, s60
	s_cmp_lg_u32 s37, s39
	s_waitcnt lgkmcnt(0)
	s_nop 1
	v_add_f32_dpp v46, v46, v46 quad_perm:[2,3,0,1] row_mask:0xf bank_mask:0xf
	v_add_f32_dpp v47, v47, v47 quad_perm:[2,3,0,1] row_mask:0xf bank_mask:0xf
	s_waitcnt lgkmcnt(0)
	s_nop 1
	v_add_f32_dpp v46, v46, v46 row_half_mirror row_mask:0xf bank_mask:0xf
	v_add_f32_dpp v47, v47, v47 row_half_mirror row_mask:0xf bank_mask:0xf
	s_waitcnt lgkmcnt(0)
	s_nop 1
	v_add_f32_dpp v46, v46, v46 row_mirror row_mask:0xf bank_mask:0xf
	v_add_f32_dpp v47, v47, v47 row_mirror row_mask:0xf bank_mask:0xf
	s_nop 0
	v_pk_mul_f32 v[48:49], v[46:47], s[18:19] op_sel_hi:[1,0]
	v_pk_fma_f32 v[64:65], v[46:47], s[18:19], v[78:79] op_sel_hi:[1,0,1] neg_lo:[1,0,0] neg_hi:[1,0,0]
	v_pk_add_f32 v[50:51], v[50:51], v[48:49] op_sel_hi:[1,0] neg_lo:[0,1] neg_hi:[0,1]
	v_pk_add_f32 v[68:69], v[82:83], v[48:49] op_sel:[0,1] neg_lo:[0,1] neg_hi:[0,1]
	v_pk_fma_f32 v[56:57], v[46:47], s[18:19], v[74:75] op_sel_hi:[1,0,1] neg_lo:[1,0,0] neg_hi:[1,0,0]
	v_pk_mul_f32 v[58:59], v[50:51], v[50:51]
	v_pk_mul_f32 v[46:47], v[64:65], v[64:65]
	v_pk_mul_f32 v[70:71], v[68:69], v[68:69]
	v_pk_add_f32 v[52:53], v[52:53], v[48:49] op_sel_hi:[1,0] neg_lo:[0,1] neg_hi:[0,1]
	v_pk_fma_f32 v[66:67], v[56:57], v[56:57], v[46:47]
	v_pk_add_f32 v[46:47], v[90:91], v[48:49] op_sel:[0,1] neg_lo:[0,1] neg_hi:[0,1]
	v_mov_b32_e32 v75, v58
	v_mov_b32_e32 v58, v71
	v_pk_mul_f32 v[60:61], v[52:53], v[52:53]
	v_pk_mul_f32 v[72:73], v[46:47], v[46:47]
	v_mov_b32_e32 v74, v70
	v_pk_add_f32 v[58:59], v[58:59], v[66:67] op_sel:[0,1] op_sel_hi:[1,0]
	v_pk_add_f32 v[54:55], v[54:55], v[48:49] op_sel_hi:[1,0] neg_lo:[0,1] neg_hi:[0,1]
	v_pk_add_f32 v[42:43], v[98:99], v[48:49] op_sel:[0,1] neg_lo:[0,1] neg_hi:[0,1]
	v_pk_add_f32 v[58:59], v[74:75], v[58:59]
	v_mov_b32_e32 v66, v73
	v_mov_b32_e32 v67, v61
	v_pk_mul_f32 v[62:63], v[54:55], v[54:55]
	v_pk_mul_f32 v[48:49], v[42:43], v[42:43]
	v_pk_add_f32 v[58:59], v[66:67], v[58:59]
	v_mov_b32_e32 v73, v60
	v_pk_add_f32 v[58:59], v[72:73], v[58:59]
	v_mov_b32_e32 v60, v49
	v_mov_b32_e32 v61, v63
	v_pk_add_f32 v[58:59], v[60:61], v[58:59]
	v_mov_b32_e32 v49, v62
	v_pk_add_f32 v[48:49], v[48:49], v[58:59]
	s_waitcnt lgkmcnt(0)
	s_nop 1
	v_add_f32_dpp v48, v48, v48 quad_perm:[1,0,3,2] row_mask:0xf bank_mask:0xf
	v_add_f32_dpp v49, v49, v49 quad_perm:[1,0,3,2] row_mask:0xf bank_mask:0xf
	s_waitcnt lgkmcnt(0)
	s_nop 1
	v_add_f32_dpp v48, v48, v48 quad_perm:[2,3,0,1] row_mask:0xf bank_mask:0xf
	v_add_f32_dpp v49, v49, v49 quad_perm:[2,3,0,1] row_mask:0xf bank_mask:0xf
	s_waitcnt lgkmcnt(0)
	s_nop 1
	v_add_f32_dpp v48, v48, v48 row_half_mirror row_mask:0xf bank_mask:0xf
	v_add_f32_dpp v49, v49, v49 row_half_mirror row_mask:0xf bank_mask:0xf
	s_waitcnt lgkmcnt(0)
	s_nop 1
	v_add_f32_dpp v48, v48, v48 row_mirror row_mask:0xf bank_mask:0xf
	v_add_f32_dpp v49, v49, v49 row_mirror row_mask:0xf bank_mask:0xf
	v_mov_b64_e32 v[58:59], s[2:3]
	v_pk_fma_f32 v[48:49], v[48:49], s[18:19], v[58:59] op_sel_hi:[1,0,0]
	s_mov_b32 s2, 0xfcc8000
	v_mul_f32_e32 v60, 0x4b800000, v49
	v_cmp_gt_f32_e64 s[74:75], s33, v49
	s_nop 1
	v_cndmask_b32_e64 v49, v49, v60, s[74:75]
	v_rsq_f32_e32 v49, v49
	s_nop 0
	v_mul_f32_e32 v60, 0x45800000, v49
	v_cndmask_b32_e64 v49, v49, v60, s[74:75]
	v_mul_f32_e32 v50, v50, v49
	v_cvt_pk_bf16_f32 v50, v50, s0
	ds_write_b16 v249, v50 offset:96
	v_mul_f32_e32 v50, v53, v49
	v_cvt_pk_bf16_f32 v50, v50, s0
	v_mul_f32_e32 v56, v56, v49
	ds_write_b16 v249, v50 offset:128
	v_mul_f32_e32 v50, v52, v49
	v_cvt_pk_bf16_f32 v56, v56, s0
	v_cvt_pk_bf16_f32 v50, v50, s0
	ds_write_b16 v249, v56
	v_mul_f32_e32 v56, v64, v49
	v_mul_f32_e32 v51, v51, v49
	ds_write_b16 v249, v50 offset:160
	v_mul_f32_e32 v50, v55, v49
	v_mul_f32_e32 v52, v54, v49
	v_mul_f32_e32 v49, 0x4b800000, v48
	v_cmp_gt_f32_e64 s[74:75], s33, v48
	v_cvt_pk_bf16_f32 v51, v51, s0
	v_cvt_pk_bf16_f32 v50, v50, s0
	v_cndmask_b32_e64 v48, v48, v49, s[74:75]
	v_rsq_f32_e32 v53, v48
	v_pk_add_f32 v[48:49], v[76:77], 0 op_sel_hi:[1,0]
	ds_write_b16 v249, v51 offset:64
	v_pk_add_f32 v[48:49], v[48:49], v[80:81]
	ds_write_b16 v249, v50 offset:192
	v_pk_add_f32 v[48:49], v[48:49], v[84:85]
	v_cvt_pk_bf16_f32 v52, v52, s0
	v_pk_add_f32 v[48:49], v[48:49], v[88:89]
	ds_write_b16 v249, v52 offset:224
	v_pk_add_f32 v[48:49], v[48:49], v[92:93]
	v_mul_f32_e32 v52, 0x45800000, v53
	v_pk_add_f32 v[48:49], v[48:49], v[96:97]
	v_cndmask_b32_e64 v82, v53, v52, s[74:75]
	v_pk_add_f32 v[48:49], v[48:49], v[100:101]
	v_mul_f32_e32 v52, v57, v82
	v_pk_add_f32 v[48:49], v[48:49], v[44:45]
	v_cvt_pk_bf16_f32 v52, v52, s0
	ds_write_b16 v249, v52 offset:272
	v_mul_f32_e32 v52, v65, v82
	v_cvt_pk_bf16_f32 v83, v52, s0
	s_waitcnt lgkmcnt(1)
; #define LAS __attribute__((address_space(3)))
; __device__ __forceinline__ bf16_t f2bf(float f) { return (bf16_t)(pk2(f, 0.f) & 0xffffu); }
; __device__ __forceinline__ void ret_out_phase(const Args& A, Frame& F, int l, bool lastl, bf16_t* ARET, bf16_t* ALRU) {
;     ...
; #pragma unroll
;         for (int r = 0; r < 4; ++r) {
;             float sm = 0.f;
; #pragma unroll
;             for (int dvt = 0; dvt < 8; ++dvt) sm += O[dvt][r];
;             const float mu = sum16(sm) * (1.f / DV);
;             float q2 = 0.f;
; #pragma unroll
;             for (int dvt = 0; dvt < 8; ++dvt) { const float dd = O[dvt][r] - mu; q2 += dd * dd; }
;             const float rstd = rsqrtf(sum16(q2) * (1.f / DV) + EPS);
; #pragma unroll
;             for (int dvt = 0; dvt < 8; ++dvt) os[(16 * w + 4 * fq + r) * 136 + 16 * dvt + fr] = f2bf((O[dvt][r] - mu) * rstd);
;         }
;         __builtin_amdgcn_fence(__ATOMIC_RELEASE, "workgroup"); __builtin_amdgcn_wave_barrier(); __builtin_amdgcn_fence(__ATOMIC_ACQUIRE, "workgroup");
;         {
;             const int rr = 16 * w + (lane >> 2), cc = (lane & 3) * 32;
;             const size_t go = (rowbase + rr) * D + 128 * h + cc;
; #pragma unroll
;             for (int i = 0; i < 4; ++i) {
;                 const u32x4 ov = *(const LAS u32x4*)(os + rr * 136 + cc + 8 * i);
;                 const u32x4 gv = *(const u32x4*)(WSB(WS_SG) + go + 8 * i);
	s_nop 1
	v_add_f32_dpp v48, v48, v48 quad_perm:[1,0,3,2] row_mask:0xf bank_mask:0xf
	v_add_f32_dpp v49, v49, v49 quad_perm:[1,0,3,2] row_mask:0xf bank_mask:0xf
	v_mov_b32_e32 v52, v88
	v_mov_b32_e32 v53, v84
	v_mov_b32_e32 v84, v89
	v_mov_b32_e32 v54, v96
	s_waitcnt lgkmcnt(0)
	s_nop 1
	v_add_f32_dpp v48, v48, v48 quad_perm:[2,3,0,1] row_mask:0xf bank_mask:0xf
	v_add_f32_dpp v49, v49, v49 quad_perm:[2,3,0,1] row_mask:0xf bank_mask:0xf
	v_mov_b32_e32 v55, v92
	v_mov_b32_e32 v92, v97
	v_cvt_pk_bf16_f32 v56, v56, s0
	ds_write_b16 v249, v56 offset:32
	s_waitcnt lgkmcnt(1)
	s_nop 1
	v_add_f32_dpp v48, v48, v48 row_half_mirror row_mask:0xf bank_mask:0xf
	v_add_f32_dpp v49, v49, v49 row_half_mirror row_mask:0xf bank_mask:0xf
	v_mov_b32_e32 v56, v44
	v_mov_b32_e32 v57, v100
	v_mov_b32_e32 v100, v45
	v_mul_f32_e32 v47, v47, v82
	s_waitcnt lgkmcnt(0)
	s_nop 1
	v_add_f32_dpp v48, v48, v48 row_mirror row_mask:0xf bank_mask:0xf
	v_add_f32_dpp v49, v49, v49 row_mirror row_mask:0xf bank_mask:0xf
	v_cvt_pk_bf16_f32 v47, v47, s0
	v_pk_mul_f32 v[50:51], v[48:49], s[18:19] op_sel_hi:[1,0]
	v_pk_fma_f32 v[66:67], v[48:49], s[18:19], v[76:77] op_sel_hi:[1,0,1] neg_lo:[1,0,0] neg_hi:[1,0,0]
	v_pk_add_f32 v[52:53], v[52:53], v[50:51] op_sel_hi:[1,0] neg_lo:[0,1] neg_hi:[0,1]
	v_pk_fma_f32 v[48:49], v[48:49], s[18:19], v[80:81] op_sel_hi:[1,0,1] neg_lo:[1,0,0] neg_hi:[1,0,0]
	v_pk_add_f32 v[72:73], v[84:85], v[50:51] op_sel:[0,1] neg_lo:[0,1] neg_hi:[0,1]
	v_pk_mul_f32 v[60:61], v[52:53], v[52:53]
	v_pk_mul_f32 v[70:71], v[48:49], v[48:49]
	v_pk_mul_f32 v[74:75], v[72:73], v[72:73]
	v_pk_add_f32 v[54:55], v[54:55], v[50:51] op_sel_hi:[1,0] neg_lo:[0,1] neg_hi:[0,1]
	v_pk_fma_f32 v[70:71], v[66:67], v[66:67], v[70:71]
	v_pk_add_f32 v[76:77], v[92:93], v[50:51] op_sel:[0,1] neg_lo:[0,1] neg_hi:[0,1]
	v_mov_b32_e32 v81, v60
	v_mov_b32_e32 v60, v75
	v_pk_mul_f32 v[62:63], v[54:55], v[54:55]
	v_pk_mul_f32 v[78:79], v[76:77], v[76:77]
	v_mov_b32_e32 v80, v74
	v_pk_add_f32 v[60:61], v[60:61], v[70:71] op_sel:[0,1] op_sel_hi:[1,0]
	v_pk_add_f32 v[56:57], v[56:57], v[50:51] op_sel_hi:[1,0] neg_lo:[0,1] neg_hi:[0,1]
	v_pk_add_f32 v[44:45], v[100:101], v[50:51] op_sel:[0,1] neg_lo:[0,1] neg_hi:[0,1]
	v_pk_add_f32 v[60:61], v[80:81], v[60:61]
	v_mov_b32_e32 v70, v79
	v_mov_b32_e32 v71, v63
	v_pk_mul_f32 v[64:65], v[56:57], v[56:57]
	v_pk_mul_f32 v[50:51], v[44:45], v[44:45]
	v_pk_add_f32 v[60:61], v[70:71], v[60:61]
	v_mov_b32_e32 v79, v62
	v_pk_add_f32 v[60:61], v[78:79], v[60:61]
	v_mov_b32_e32 v62, v51
	v_mov_b32_e32 v63, v65
	v_pk_add_f32 v[60:61], v[62:63], v[60:61]
	v_mov_b32_e32 v51, v64
	v_pk_add_f32 v[50:51], v[50:51], v[60:61]
	v_mul_f32_e32 v62, v69, v82
	v_cvt_pk_bf16_f32 v62, v62, s0
	ds_write_b16 v249, v62 offset:336
	v_mul_f32_e32 v62, v68, v82
	s_waitcnt lgkmcnt(1)
	s_nop 1
	v_add_f32_dpp v50, v50, v50 quad_perm:[1,0,3,2] row_mask:0xf bank_mask:0xf
	v_add_f32_dpp v51, v51, v51 quad_perm:[1,0,3,2] row_mask:0xf bank_mask:0xf
	v_cvt_pk_bf16_f32 v62, v62, s0
	v_mul_f32_e32 v46, v46, v82
	ds_write_b16 v249, v62 offset:368
	ds_write_b16 v249, v47 offset:400
	s_waitcnt lgkmcnt(2)
	s_nop 1
	v_add_f32_dpp v50, v50, v50 quad_perm:[2,3,0,1] row_mask:0xf bank_mask:0xf
	v_add_f32_dpp v51, v51, v51 quad_perm:[2,3,0,1] row_mask:0xf bank_mask:0xf
	v_cvt_pk_bf16_f32 v62, v46, s0
	v_mul_f32_e32 v43, v43, v82
	v_cvt_pk_bf16_f32 v43, v43, s0
	ds_write_b16 v249, v43 offset:464
	s_waitcnt lgkmcnt(1)
	s_nop 1
	v_add_f32_dpp v46, v50, v50 row_half_mirror row_mask:0xf bank_mask:0xf
	v_add_f32_dpp v47, v51, v51 row_half_mirror row_mask:0xf bank_mask:0xf
	v_mul_f32_e32 v42, v42, v82
	v_cvt_pk_bf16_f32 v42, v42, s0
	ds_write_b16 v249, v42 offset:496
	ds_write_b16 v249, v83 offset:304
	s_waitcnt lgkmcnt(2)
	s_nop 1
	v_add_f32_dpp v46, v46, v46 row_mirror row_mask:0xf bank_mask:0xf
	v_add_f32_dpp v47, v47, v47 row_mirror row_mask:0xf bank_mask:0xf
	ds_write_b16 v249, v62 offset:432
	v_pk_fma_f32 v[46:47], v[46:47], s[18:19], v[58:59] op_sel_hi:[1,0,0]
	s_nop 0
	v_mul_f32_e32 v43, 0x4b800000, v47
	v_cmp_gt_f32_e64 s[74:75], s33, v47
	s_nop 1
	v_cndmask_b32_e64 v43, v47, v43, s[74:75]
	v_rsq_f32_e32 v43, v43
	s_nop 0
	v_mul_f32_e32 v42, 0x45800000, v43
	v_cndmask_b32_e64 v42, v43, v42, s[74:75]
	v_mul_f32_e32 v43, v66, v42
	v_cvt_pk_bf16_f32 v43, v43, s0
	ds_write_b16 v249, v43 offset:544
	v_mul_f32_e32 v43, v48, v42
	v_cvt_pk_bf16_f32 v43, v43, s0
	ds_write_b16 v249, v43 offset:576
	v_mul_f32_e32 v43, v53, v42
	v_cvt_pk_bf16_f32 v43, v43, s0
	ds_write_b16 v249, v43 offset:608
	v_mul_f32_e32 v43, v52, v42
	v_cvt_pk_bf16_f32 v43, v43, s0
	ds_write_b16 v249, v43 offset:640
	v_mul_f32_e32 v43, v55, v42
	v_cvt_pk_bf16_f32 v43, v43, s0
	ds_write_b16 v249, v43 offset:672
	v_mul_f32_e32 v43, v54, v42
	v_cvt_pk_bf16_f32 v43, v43, s0
	ds_write_b16 v249, v43 offset:704
	v_mul_f32_e32 v43, v57, v42
	v_cvt_pk_bf16_f32 v43, v43, s0
	ds_write_b16 v249, v43 offset:736
	v_mul_f32_e32 v43, 0x4b800000, v46
	v_cmp_gt_f32_e64 s[74:75], s33, v46
	v_mul_f32_e32 v42, v56, v42
	v_cvt_pk_bf16_f32 v42, v42, s0
	v_cndmask_b32_e64 v43, v46, v43, s[74:75]
	v_rsq_f32_e32 v43, v43
	ds_write_b16 v249, v42 offset:768
	v_mul_f32_e32 v42, 0x45800000, v43
	v_cndmask_b32_e64 v42, v43, v42, s[74:75]
	v_mul_f32_e32 v43, v67, v42
	v_cvt_pk_bf16_f32 v43, v43, s0
	ds_write_b16 v249, v43 offset:816
	v_mul_f32_e32 v43, v49, v42
	v_cvt_pk_bf16_f32 v43, v43, s0
	ds_write_b16 v249, v43 offset:848
	v_mul_f32_e32 v43, v73, v42
	v_cvt_pk_bf16_f32 v43, v43, s0
	ds_write_b16 v249, v43 offset:880
	v_mul_f32_e32 v43, v72, v42
	v_cvt_pk_bf16_f32 v43, v43, s0
	ds_write_b16 v249, v43 offset:912
	v_mul_f32_e32 v43, v77, v42
	v_cvt_pk_bf16_f32 v43, v43, s0
	ds_write_b16 v249, v43 offset:944
	v_mul_f32_e32 v43, v76, v42
	v_cvt_pk_bf16_f32 v43, v43, s0
	ds_write_b16 v249, v43 offset:976
	v_mul_f32_e32 v43, v45, v42
	v_mul_f32_e32 v42, v44, v42
	v_cvt_pk_bf16_f32 v43, v43, s0
	v_cvt_pk_bf16_f32 v42, v42, s0
	ds_write_b16 v249, v43 offset:1008
	ds_write_b16 v249, v42 offset:1040
	v_lshl_add_u64 v[42:43], s[8:9], 0, v[124:125]
	v_lshlrev_b64 v[42:43], 10, v[42:43]
	v_or_b32_e32 v42, v42, v126
	v_or_b32_e32 v42, s82, v42
	v_lshlrev_b64 v[54:55], 1, v[42:43]
	v_lshl_add_u64 v[42:43], s[50:51], 0, v[54:55]
	s_waitcnt lgkmcnt(0)
; #define LAS __attribute__((address_space(3)))
; __device__ __forceinline__ unsigned pk2(float lo, float hi) { const f32x2_t v = {lo, hi}; const bf16v2_t b = __builtin_convertvector(v, bf16v2_t); return __builtin_bit_cast(unsigned, b); }
; __device__ __forceinline__ float bflo(unsigned u) { return __uint_as_float(u << 16); }
; __device__ __forceinline__ float bfhi(unsigned u) { return __uint_as_float(u & 0xffff0000u); }
; __device__ __forceinline__ void ret_out_phase(const Args& A, Frame& F, int l, bool lastl, bf16_t* ARET, bf16_t* ALRU) {
;     ...
;         {
;             const int rr = 16 * w + (lane >> 2), cc = (lane & 3) * 32;
;             const size_t go = (rowbase + rr) * D + 128 * h + cc;
; #pragma unroll
;             for (int i = 0; i < 4; ++i) {
;                 const u32x4 ov = *(const LAS u32x4*)(os + rr * 136 + cc + 8 * i);
;                 const u32x4 gv = *(const u32x4*)(WSB(WS_SG) + go + 8 * i);
;                 u32x4 rv;
; #pragma unroll
;                 for (int e = 0; e < 4; ++e) rv[e] = pk2(bflo(ov[e]) * bflo(gv[e]), bfhi(ov[e]) * bfhi(gv[e]));
;                 *(u32x4*)(ARET + go + 8 * i) = rv;
;             }
;         }
; #pragma unroll
;         for (int i = 0; i < 4; ++i) {
;             const int u = tid + i * NTHREADS, r = u >> 4, c8 = (u & 15) * 8;
;             const size_t o = (rowbase + r) * D + 128 * h + c8;
;             const u32x4 hf = *(const u32x4*)(WSB(WS_HF) + o), hb = *(const u32x4*)(WSB(WS_HB) + o), gg = *(const u32x4*)(WSB(WS_GG) + o);
;             u32x4 ov;
; #pragma unroll
;             for (int e = 0; e < 4; ++e) ov[e] = pk2((bflo(hf[e]) + bflo(hb[e])) * bflo(gg[e]), (bfhi(hf[e]) + bfhi(hb[e])) * bfhi(gg[e]));
;             *(u32x4*)(ALRU + o) = ov;
;         }
	v_add_u32_e32 v129, s8, v124
	v_lshlrev_b32_e32 v129, 11, v129
	v_lshrrev_b32_e32 v131, 2, v126
	v_or_b32_e32 v100, s82, v131
	v_lshl_or_b32 v129, v100, 1, v129
	v_mul_u32_u24_e32 v132, 6, v131
	v_sub_u32_e32 v130, v133, v132
	v_or_b32_e32 v100, s82, v104
	v_add_u32_e32 v141, s8, v106
	v_lshlrev_b32_e32 v141, 11, v141
	v_lshl_or_b32 v141, v100, 1, v141
	v_add_u32_e32 v250, s8, v108
	v_lshlrev_b32_e32 v250, 11, v250
	v_lshl_or_b32 v250, v100, 1, v250
	v_add_u32_e32 v251, s8, v110
	v_lshlrev_b32_e32 v251, 11, v251
	v_lshl_or_b32 v251, v100, 1, v251
	v_add_u32_e32 v252, s8, v112
	v_lshlrev_b32_e32 v252, 11, v252
	v_lshl_or_b32 v252, v100, 1, v252
	global_load_dwordx4 v[56:59], v129, s[50:51]
	global_load_dwordx4 v[60:63], v129, s[50:51] offset:64
	global_load_dwordx4 v[64:67], v129, s[50:51] offset:128
	global_load_dwordx4 v[68:71], v129, s[50:51] offset:192
	global_load_dwordx4 v[72:75], v141, s[10:11]
	global_load_dwordx4 v[76:79], v141, s[12:13]
	global_load_dwordx4 v[80:83], v141, s[14:15]
	global_load_dwordx4 v[84:87], v250, s[10:11]
	global_load_dwordx4 v[88:91], v250, s[12:13]
	global_load_dwordx4 v[92:95], v250, s[14:15]
	ds_read_b128 v[96:99], v130
	ds_read_b128 v[44:47], v130 offset:64
	s_waitcnt vmcnt(9) lgkmcnt(1)
	v_lshlrev_b32_e32 v100, 16, v96
	v_and_b32_e32 v101, 0xffff0000, v96
	v_lshlrev_b32_e32 v52, 16, v56
	v_and_b32_e32 v53, 0xffff0000, v56
	v_pk_mul_f32 v[100:101], v[100:101], v[52:53]
	s_nop 0
	v_cvt_pk_bf16_f32 v56, v100, v101
	v_lshlrev_b32_e32 v100, 16, v97
	v_and_b32_e32 v101, 0xffff0000, v97
	v_lshlrev_b32_e32 v52, 16, v57
	v_and_b32_e32 v53, 0xffff0000, v57
	v_pk_mul_f32 v[100:101], v[100:101], v[52:53]
	s_nop 0
	v_cvt_pk_bf16_f32 v57, v100, v101
	v_lshlrev_b32_e32 v100, 16, v98
	v_and_b32_e32 v101, 0xffff0000, v98
	v_lshlrev_b32_e32 v52, 16, v58
	v_and_b32_e32 v53, 0xffff0000, v58
	v_pk_mul_f32 v[100:101], v[100:101], v[52:53]
	s_nop 0
	v_cvt_pk_bf16_f32 v58, v100, v101
	v_lshlrev_b32_e32 v100, 16, v99
	v_and_b32_e32 v101, 0xffff0000, v99
	v_lshlrev_b32_e32 v52, 16, v59
	v_and_b32_e32 v53, 0xffff0000, v59
	v_pk_mul_f32 v[100:101], v[100:101], v[52:53]
	s_nop 0
	v_cvt_pk_bf16_f32 v59, v100, v101
	global_store_dwordx4 v129, v[56:59], s[88:89]
	s_waitcnt vmcnt(9) lgkmcnt(0)
	v_lshlrev_b32_e32 v100, 16, v44
	v_and_b32_e32 v101, 0xffff0000, v44
	v_lshlrev_b32_e32 v52, 16, v60
	v_and_b32_e32 v53, 0xffff0000, v60
	v_pk_mul_f32 v[100:101], v[100:101], v[52:53]
	s_nop 0
	v_cvt_pk_bf16_f32 v60, v100, v101
	v_lshlrev_b32_e32 v100, 16, v45
	v_and_b32_e32 v101, 0xffff0000, v45
	v_lshlrev_b32_e32 v52, 16, v61
	v_and_b32_e32 v53, 0xffff0000, v61
	v_pk_mul_f32 v[100:101], v[100:101], v[52:53]
	s_nop 0
	v_cvt_pk_bf16_f32 v61, v100, v101
	v_lshlrev_b32_e32 v100, 16, v46
	v_and_b32_e32 v101, 0xffff0000, v46
	v_lshlrev_b32_e32 v52, 16, v62
	v_and_b32_e32 v53, 0xffff0000, v62
	v_pk_mul_f32 v[100:101], v[100:101], v[52:53]
	s_nop 0
	v_cvt_pk_bf16_f32 v62, v100, v101
	v_lshlrev_b32_e32 v100, 16, v47
	v_and_b32_e32 v101, 0xffff0000, v47
	v_lshlrev_b32_e32 v52, 16, v63
	v_and_b32_e32 v53, 0xffff0000, v63
	v_pk_mul_f32 v[100:101], v[100:101], v[52:53]
	s_nop 0
	v_cvt_pk_bf16_f32 v63, v100, v101
	global_store_dwordx4 v129, v[60:63], s[88:89] offset:64
	ds_read_b128 v[96:99], v130 offset:128
	ds_read_b128 v[44:47], v130 offset:192
	s_waitcnt vmcnt(9) lgkmcnt(1)
	v_lshlrev_b32_e32 v100, 16, v96
	v_and_b32_e32 v101, 0xffff0000, v96
	v_lshlrev_b32_e32 v52, 16, v64
	v_and_b32_e32 v53, 0xffff0000, v64
	v_pk_mul_f32 v[100:101], v[100:101], v[52:53]
	s_nop 0
	v_cvt_pk_bf16_f32 v64, v100, v101
	v_lshlrev_b32_e32 v100, 16, v97
	v_and_b32_e32 v101, 0xffff0000, v97
	v_lshlrev_b32_e32 v52, 16, v65
	v_and_b32_e32 v53, 0xffff0000, v65
	v_pk_mul_f32 v[100:101], v[100:101], v[52:53]
	s_nop 0
	v_cvt_pk_bf16_f32 v65, v100, v101
	v_lshlrev_b32_e32 v100, 16, v98
	v_and_b32_e32 v101, 0xffff0000, v98
	v_lshlrev_b32_e32 v52, 16, v66
	v_and_b32_e32 v53, 0xffff0000, v66
	v_pk_mul_f32 v[100:101], v[100:101], v[52:53]
	s_nop 0
	v_cvt_pk_bf16_f32 v66, v100, v101
	v_lshlrev_b32_e32 v100, 16, v99
	v_and_b32_e32 v101, 0xffff0000, v99
	v_lshlrev_b32_e32 v52, 16, v67
	v_and_b32_e32 v53, 0xffff0000, v67
	v_pk_mul_f32 v[100:101], v[100:101], v[52:53]
	s_nop 0
	v_cvt_pk_bf16_f32 v67, v100, v101
	global_store_dwordx4 v129, v[64:67], s[88:89] offset:128
	s_waitcnt vmcnt(9) lgkmcnt(0)
	v_lshlrev_b32_e32 v100, 16, v44
	v_and_b32_e32 v101, 0xffff0000, v44
	v_lshlrev_b32_e32 v52, 16, v68
	v_and_b32_e32 v53, 0xffff0000, v68
	v_pk_mul_f32 v[100:101], v[100:101], v[52:53]
	s_nop 0
	v_cvt_pk_bf16_f32 v68, v100, v101
	v_lshlrev_b32_e32 v100, 16, v45
	v_and_b32_e32 v101, 0xffff0000, v45
	v_lshlrev_b32_e32 v52, 16, v69
	v_and_b32_e32 v53, 0xffff0000, v69
	v_pk_mul_f32 v[100:101], v[100:101], v[52:53]
	s_nop 0
	v_cvt_pk_bf16_f32 v69, v100, v101
	v_lshlrev_b32_e32 v100, 16, v46
	v_and_b32_e32 v101, 0xffff0000, v46
	v_lshlrev_b32_e32 v52, 16, v70
	v_and_b32_e32 v53, 0xffff0000, v70
	v_pk_mul_f32 v[100:101], v[100:101], v[52:53]
	s_nop 0
	v_cvt_pk_bf16_f32 v70, v100, v101
	v_lshlrev_b32_e32 v100, 16, v47
	v_and_b32_e32 v101, 0xffff0000, v47
	v_lshlrev_b32_e32 v52, 16, v71
	v_and_b32_e32 v53, 0xffff0000, v71
	v_pk_mul_f32 v[100:101], v[100:101], v[52:53]
	s_nop 0
	v_cvt_pk_bf16_f32 v71, v100, v101
	global_store_dwordx4 v129, v[68:71], s[88:89] offset:192
	s_nop 1
	global_load_dwordx4 v[56:59], v251, s[10:11]
	global_load_dwordx4 v[60:63], v251, s[12:13]
	global_load_dwordx4 v[64:67], v251, s[14:15]
	global_load_dwordx4 v[68:71], v252, s[10:11]
	global_load_dwordx4 v[44:47], v252, s[12:13]
	global_load_dwordx4 v[48:51], v252, s[14:15]
	s_waitcnt vmcnt(13)
; __device__ __forceinline__ unsigned pk2(float lo, float hi) { const f32x2_t v = {lo, hi}; const bf16v2_t b = __builtin_convertvector(v, bf16v2_t); return __builtin_bit_cast(unsigned, b); }
; __device__ __forceinline__ float bflo(unsigned u) { return __uint_as_float(u << 16); }
; __device__ __forceinline__ float bfhi(unsigned u) { return __uint_as_float(u & 0xffff0000u); }
; __device__ __forceinline__ void ret_out_phase(const Args& A, Frame& F, int l, bool lastl, bf16_t* ARET, bf16_t* ALRU) {
;     ...
; #pragma unroll
;         for (int i = 0; i < 4; ++i) {
;             const int u = tid + i * NTHREADS, r = u >> 4, c8 = (u & 15) * 8;
;             const size_t o = (rowbase + r) * D + 128 * h + c8;
;             const u32x4 hf = *(const u32x4*)(WSB(WS_HF) + o), hb = *(const u32x4*)(WSB(WS_HB) + o), gg = *(const u32x4*)(WSB(WS_GG) + o);
;             u32x4 ov;
; #pragma unroll
;             for (int e = 0; e < 4; ++e) ov[e] = pk2((bflo(hf[e]) + bflo(hb[e])) * bflo(gg[e]), (bfhi(hf[e]) + bfhi(hb[e])) * bfhi(gg[e]));
;             *(u32x4*)(ALRU + o) = ov;
;         }
	v_lshlrev_b32_e32 v100, 16, v72
	v_and_b32_e32 v101, 0xffff0000, v72
	v_lshlrev_b32_e32 v52, 16, v76
	v_and_b32_e32 v53, 0xffff0000, v76
	v_pk_add_f32 v[100:101], v[100:101], v[52:53]
	v_lshlrev_b32_e32 v52, 16, v80
	v_and_b32_e32 v53, 0xffff0000, v80
	v_pk_mul_f32 v[100:101], v[100:101], v[52:53]
	s_nop 0
	v_cvt_pk_bf16_f32 v72, v100, v101
	v_lshlrev_b32_e32 v100, 16, v73
	v_and_b32_e32 v101, 0xffff0000, v73
	v_lshlrev_b32_e32 v52, 16, v77
	v_and_b32_e32 v53, 0xffff0000, v77
	v_pk_add_f32 v[100:101], v[100:101], v[52:53]
	v_lshlrev_b32_e32 v52, 16, v81
	v_and_b32_e32 v53, 0xffff0000, v81
	v_pk_mul_f32 v[100:101], v[100:101], v[52:53]
	s_nop 0
	v_cvt_pk_bf16_f32 v73, v100, v101
	v_lshlrev_b32_e32 v100, 16, v74
	v_and_b32_e32 v101, 0xffff0000, v74
	v_lshlrev_b32_e32 v52, 16, v78
	v_and_b32_e32 v53, 0xffff0000, v78
	v_pk_add_f32 v[100:101], v[100:101], v[52:53]
	v_lshlrev_b32_e32 v52, 16, v82
	v_and_b32_e32 v53, 0xffff0000, v82
	v_pk_mul_f32 v[100:101], v[100:101], v[52:53]
	s_nop 0
	v_cvt_pk_bf16_f32 v74, v100, v101
	v_lshlrev_b32_e32 v100, 16, v75
	v_and_b32_e32 v101, 0xffff0000, v75
	v_lshlrev_b32_e32 v52, 16, v79
	v_and_b32_e32 v53, 0xffff0000, v79
	v_pk_add_f32 v[100:101], v[100:101], v[52:53]
	v_lshlrev_b32_e32 v52, 16, v83
	v_and_b32_e32 v53, 0xffff0000, v83
	v_pk_mul_f32 v[100:101], v[100:101], v[52:53]
	s_nop 0
	v_cvt_pk_bf16_f32 v75, v100, v101
	global_store_dwordx4 v141, v[72:75], s[90:91]
	s_waitcnt vmcnt(11)
	v_lshlrev_b32_e32 v100, 16, v84
	v_and_b32_e32 v101, 0xffff0000, v84
	v_lshlrev_b32_e32 v52, 16, v88
	v_and_b32_e32 v53, 0xffff0000, v88
	v_pk_add_f32 v[100:101], v[100:101], v[52:53]
	v_lshlrev_b32_e32 v52, 16, v92
	v_and_b32_e32 v53, 0xffff0000, v92
	v_pk_mul_f32 v[100:101], v[100:101], v[52:53]
	s_nop 0
	v_cvt_pk_bf16_f32 v84, v100, v101
	v_lshlrev_b32_e32 v100, 16, v85
	v_and_b32_e32 v101, 0xffff0000, v85
	v_lshlrev_b32_e32 v52, 16, v89
	v_and_b32_e32 v53, 0xffff0000, v89
	v_pk_add_f32 v[100:101], v[100:101], v[52:53]
	v_lshlrev_b32_e32 v52, 16, v93
	v_and_b32_e32 v53, 0xffff0000, v93
	v_pk_mul_f32 v[100:101], v[100:101], v[52:53]
	s_nop 0
	v_cvt_pk_bf16_f32 v85, v100, v101
	v_lshlrev_b32_e32 v100, 16, v86
	v_and_b32_e32 v101, 0xffff0000, v86
	v_lshlrev_b32_e32 v52, 16, v90
	v_and_b32_e32 v53, 0xffff0000, v90
	v_pk_add_f32 v[100:101], v[100:101], v[52:53]
	v_lshlrev_b32_e32 v52, 16, v94
	v_and_b32_e32 v53, 0xffff0000, v94
	v_pk_mul_f32 v[100:101], v[100:101], v[52:53]
	s_nop 0
	v_cvt_pk_bf16_f32 v86, v100, v101
	v_lshlrev_b32_e32 v100, 16, v87
	v_and_b32_e32 v101, 0xffff0000, v87
	v_lshlrev_b32_e32 v52, 16, v91
	v_and_b32_e32 v53, 0xffff0000, v91
	v_pk_add_f32 v[100:101], v[100:101], v[52:53]
	v_lshlrev_b32_e32 v52, 16, v95
	v_and_b32_e32 v53, 0xffff0000, v95
	v_pk_mul_f32 v[100:101], v[100:101], v[52:53]
	s_nop 0
	v_cvt_pk_bf16_f32 v87, v100, v101
	global_store_dwordx4 v250, v[84:87], s[90:91]
	s_waitcnt vmcnt(5)
	v_lshlrev_b32_e32 v100, 16, v56
	v_and_b32_e32 v101, 0xffff0000, v56
	v_lshlrev_b32_e32 v52, 16, v60
	v_and_b32_e32 v53, 0xffff0000, v60
	v_pk_add_f32 v[100:101], v[100:101], v[52:53]
	v_lshlrev_b32_e32 v52, 16, v64
	v_and_b32_e32 v53, 0xffff0000, v64
	v_pk_mul_f32 v[100:101], v[100:101], v[52:53]
	s_nop 0
	v_cvt_pk_bf16_f32 v56, v100, v101
	v_lshlrev_b32_e32 v100, 16, v57
	v_and_b32_e32 v101, 0xffff0000, v57
	v_lshlrev_b32_e32 v52, 16, v61
	v_and_b32_e32 v53, 0xffff0000, v61
	v_pk_add_f32 v[100:101], v[100:101], v[52:53]
	v_lshlrev_b32_e32 v52, 16, v65
	v_and_b32_e32 v53, 0xffff0000, v65
	v_pk_mul_f32 v[100:101], v[100:101], v[52:53]
	s_nop 0
	v_cvt_pk_bf16_f32 v57, v100, v101
	v_lshlrev_b32_e32 v100, 16, v58
	v_and_b32_e32 v101, 0xffff0000, v58
	v_lshlrev_b32_e32 v52, 16, v62
	v_and_b32_e32 v53, 0xffff0000, v62
	v_pk_add_f32 v[100:101], v[100:101], v[52:53]
	v_lshlrev_b32_e32 v52, 16, v66
	v_and_b32_e32 v53, 0xffff0000, v66
	v_pk_mul_f32 v[100:101], v[100:101], v[52:53]
	s_nop 0
	v_cvt_pk_bf16_f32 v58, v100, v101
	v_lshlrev_b32_e32 v100, 16, v59
	v_and_b32_e32 v101, 0xffff0000, v59
	v_lshlrev_b32_e32 v52, 16, v63
	v_and_b32_e32 v53, 0xffff0000, v63
	v_pk_add_f32 v[100:101], v[100:101], v[52:53]
	v_lshlrev_b32_e32 v52, 16, v67
	v_and_b32_e32 v53, 0xffff0000, v67
	v_pk_mul_f32 v[100:101], v[100:101], v[52:53]
	s_nop 0
	v_cvt_pk_bf16_f32 v59, v100, v101
	global_store_dwordx4 v251, v[56:59], s[90:91]
	s_waitcnt vmcnt(3)
	v_lshlrev_b32_e32 v100, 16, v68
	v_and_b32_e32 v101, 0xffff0000, v68
	v_lshlrev_b32_e32 v52, 16, v44
	v_and_b32_e32 v53, 0xffff0000, v44
	v_pk_add_f32 v[100:101], v[100:101], v[52:53]
	v_lshlrev_b32_e32 v52, 16, v48
	v_and_b32_e32 v53, 0xffff0000, v48
	v_pk_mul_f32 v[100:101], v[100:101], v[52:53]
	s_nop 0
	v_cvt_pk_bf16_f32 v68, v100, v101
	v_lshlrev_b32_e32 v100, 16, v69
	v_and_b32_e32 v101, 0xffff0000, v69
	v_lshlrev_b32_e32 v52, 16, v45
	v_and_b32_e32 v53, 0xffff0000, v45
	v_pk_add_f32 v[100:101], v[100:101], v[52:53]
	v_lshlrev_b32_e32 v52, 16, v49
	v_and_b32_e32 v53, 0xffff0000, v49
	v_pk_mul_f32 v[100:101], v[100:101], v[52:53]
	s_nop 0
	v_cvt_pk_bf16_f32 v69, v100, v101
	v_lshlrev_b32_e32 v100, 16, v70
	v_and_b32_e32 v101, 0xffff0000, v70
	v_lshlrev_b32_e32 v52, 16, v46
	v_and_b32_e32 v53, 0xffff0000, v46
	v_pk_add_f32 v[100:101], v[100:101], v[52:53]
	v_lshlrev_b32_e32 v52, 16, v50
	v_and_b32_e32 v53, 0xffff0000, v50
	v_pk_mul_f32 v[100:101], v[100:101], v[52:53]
	s_nop 0
	v_cvt_pk_bf16_f32 v70, v100, v101
	v_lshlrev_b32_e32 v100, 16, v71
	v_and_b32_e32 v101, 0xffff0000, v71
	v_lshlrev_b32_e32 v52, 16, v47
	v_and_b32_e32 v53, 0xffff0000, v47
	v_pk_add_f32 v[100:101], v[100:101], v[52:53]
	v_lshlrev_b32_e32 v52, 16, v51
	v_and_b32_e32 v53, 0xffff0000, v51
	v_pk_mul_f32 v[100:101], v[100:101], v[52:53]
	s_nop 0
	v_cvt_pk_bf16_f32 v71, v100, v101
	global_store_dwordx4 v252, v[68:71], s[90:91]
	s_cbranch_scc1 .LBB0_30

; #define LAS __attribute__((address_space(3)))
; __device__ __forceinline__ void cvt_load(const Frame& F, const CvtMat& m, int tt, f32x4 (&v)[4]) {
;     const int nb = m.N >> 7, kb = tt / nb, nbk = tt - kb * nb, k0 = kb * 64, n0 = nbk * 128;
;     const int src = srccol(m.kind, n0 + (F.tid & 31) * 4);
; #pragma unroll
;     for (int i = 0; i < 4; ++i) v[i] = *(const f32x4*)(m.W + (size_t)(k0 + (F.tid >> 5) + 16 * i) * m.N + src);
; }
; __device__ __forceinline__ void cvt_store(const Frame& F, const CvtMat& m, int tt, const f32x4 (&v)[4]) {
;     LAS float* tile = (LAS float*)F.lds;
;     const int nb = m.N >> 7, kb = tt / nb, nbk = tt - kb * nb, k0 = kb * 64, n0 = nbk * 128;
;     const int tid = F.tid;
; #pragma unroll
;     for (int i = 0; i < 4; ++i) {
;         const int kk = (tid >> 5) + 16 * i, nn = (tid & 31) * 4;
;         tile[kk * 129 + nn] = v[i][0]; tile[kk * 129 + nn + 1] = v[i][1]; tile[kk * 129 + nn + 2] = v[i][2]; tile[kk * 129 + nn + 3] = v[i][3];
;     }
;     __syncthreads();
;     {
;         const int n = tid >> 2, ks = (tid & 3) * 16;
;         u32x4 o0, o1;
; #pragma unroll
;         for (int i = 0; i < 4; ++i) o0[i] = pk2(tile[(ks + 2 * i) * 129 + n], tile[(ks + 2 * i + 1) * 129 + n]);
; #pragma unroll
;         for (int i = 0; i < 4; ++i) o1[i] = pk2(tile[(ks + 8 + 2 * i) * 129 + n], tile[(ks + 8 + 2 * i + 1) * 129 + n]);
;         bf16_t* dst = m.Bt + (size_t)(n0 + n) * m.K + k0 + ks;
;         *(u32x4*)dst = o0; *(u32x4*)(dst + 8) = o1;
;     }
;     __syncthreads();
; }
; __device__ __forceinline__ void convert_layer(const Args& A, Frame& F, int l) {
;     refresh(F);
;     constexpr int NT = 2 * 16 * 44 + 2 * 44 * 8 + 16 * 56 + 3 * 16 * 8;
;     const int nmy = (NT - F.bid + F.G - 1) / F.G;
;     f32x4 v[4];
;     { CvtMat m; int tt; cvt_pick(A, F, l, F.bid, m, tt); cvt_load(F, m, tt, v); }
;     for (int j = 0; j < nmy; ++j) {
;         const int it = F.bid + j * F.G, itn = (j + 1 < nmy) ? it + F.G : it;
;         f32x4 vn[4];
;         { CvtMat mn; int ttn; cvt_pick(A, F, l, itn, mn, ttn); cvt_load(F, mn, ttn, vn); }
;         { CvtMat m; int tt; cvt_pick(A, F, l, it, m, tt); cvt_store(F, m, tt, v); }
; #pragma unroll
;         for (int i = 0; i < 4; ++i) v[i] = vn[i];
;     }
.LBB0_605:
	s_abs_i32 s2, s34
	v_cvt_f32_u32_e32 v3, s2
	s_sub_i32 s10, s34, s38
	s_add_i32 s11, s10, 0xd3f
	s_sub_i32 s10, 0xfffff2c1, s10
	v_rcp_iflag_f32_e32 v3, v3
	s_xor_b32 s13, s11, s34
	s_sub_i32 s12, 0, s2
	s_max_i32 s10, s11, s10
	v_mul_f32_e32 v3, 0x4f7ffffe, v3
	v_cvt_u32_f32_e32 v3, v3
	s_ashr_i32 s11, s13, 31
	v_readfirstlane_b32 s13, v3
	s_mul_i32 s12, s12, s13
	s_mul_hi_u32 s12, s13, s12
	s_add_i32 s13, s13, s12
	s_mul_hi_u32 s12, s10, s13
	s_mul_i32 s13, s12, s2
	s_sub_i32 s10, s10, s13
	s_add_i32 s15, s12, 1
	s_sub_i32 s13, s10, s2
	s_cmp_ge_u32 s10, s2
	s_cselect_b32 s12, s15, s12
	s_cselect_b32 s10, s13, s10
	s_add_i32 s13, s12, 1
	s_cmp_ge_u32 s10, s2
	s_cselect_b32 s2, s13, s12
	s_xor_b32 s2, s2, s11
	s_sub_i32 s2, s2, s11
	s_cmp_lt_i32 s2, 1
	s_cbranch_scc1 .LBB0_691
	s_mul_hi_u32 s11, s4, s44
	s_mul_i32 s10, s4, s44
	s_lshl_b64 s[10:11], s[10:11], 2
	v_ashrrev_i32_e32 v35, 5, v0
	s_waitcnt lgkmcnt(0)
	s_add_u32 s8, s8, s10
	v_lshl_add_u32 v14, s14, 6, v35
	s_addc_u32 s9, s9, s11
	v_mad_i64_i32 v[4:5], s[10:11], v14, s5, 0
	v_ashrrev_i32_e32 v3, 31, v2
	v_lshl_add_u64 v[4:5], v[4:5], 2, s[8:9]
	v_lshlrev_b64 v[10:11], 2, v[2:3]
	v_lshl_add_u64 v[2:3], v[4:5], 0, v[10:11]
	v_add_u32_e32 v4, 16, v14
	v_add_u32_e32 v12, 32, v14
	v_add_u32_e32 v14, 48, v14
	v_mad_i64_i32 v[4:5], s[10:11], s5, v4, 0
	v_mad_i64_i32 v[12:13], s[10:11], s5, v12, 0
	v_mad_i64_i32 v[14:15], s[4:5], s5, v14, 0
	v_lshl_add_u64 v[4:5], v[4:5], 2, s[8:9]
	v_lshl_add_u64 v[12:13], v[12:13], 2, s[8:9]
	v_lshl_add_u64 v[14:15], v[14:15], 2, s[8:9]
	v_lshl_add_u64 v[6:7], v[4:5], 0, v[10:11]
	v_lshl_add_u64 v[12:13], v[12:13], 0, v[10:11]
	v_lshl_add_u64 v[14:15], v[14:15], 0, v[10:11]
	global_load_dwordx4 v[2:5], v[2:3], off
	s_nop 0
	global_load_dwordx4 v[6:9], v[6:7], off
	s_nop 0
	global_load_dwordx4 v[10:13], v[12:13], off
	s_nop 0
	global_load_dwordx4 v[14:17], v[14:15], off
	v_lshlrev_b32_e32 v22, 3, v0
	v_and_b32_e32 v22, 24, v22
	v_ashrrev_i32_e32 v36, 2, v0
	v_mul_u32_u24_e32 v25, 0x204, v22
	v_and_b32_e32 v0, -4, v0
	v_add3_u32 v37, 0, v25, v0
	v_lshrrev_b32_e32 v0, 1, v18
	s_movk_i32 s4, 0x204
	v_and_b32_e32 v0, 16, v0
	v_lshl_add_u32 v23, v34, 2, 0
	v_mul_lo_u32 v24, v35, s4
	v_and_or_b32 v38, v21, 32, v0
	v_and_b32_e32 v0, 0x60, v18
	v_or_b32_e32 v39, v20, v19
	v_or3_b32 v40, v0, v19, v20
	s_mov_b32 s20, 0
	v_add_u32_e32 v41, v23, v24
	v_lshlrev_b32_e32 v0, 1, v22
	s_mov_b32 s26, s38
	s_branch .LBB0_608
.LBB0_607:
	s_waitcnt vmcnt(7)
	ds_write2_b32 v41, v2, v3 offset1:1
	ds_write2_b32 v41, v4, v5 offset0:2 offset1:3
	v_add_u32_e32 v2, 0x2040, v41
	s_waitcnt vmcnt(6)
	ds_write2_b32 v2, v6, v7 offset1:1
	v_add_u32_e32 v2, 0x2048, v41
	ds_write2_b32 v2, v8, v9 offset1:1
	v_add_u32_e32 v2, 0x4080, v41
	s_waitcnt vmcnt(5)
	ds_write2_b32 v2, v10, v11 offset1:1
	v_add_u32_e32 v2, 0x4088, v41
	ds_write2_b32 v2, v12, v13 offset1:1
	v_add_u32_e32 v2, 0x60c0, v41
	s_waitcnt vmcnt(4)
	ds_write2_b32 v2, v14, v15 offset1:1
	v_add_u32_e32 v2, 0x60c8, v41
	v_add_u32_e32 v4, 0x400, v37
	v_add_u32_e32 v6, 0x800, v37
	ds_write2_b32 v2, v16, v17 offset1:1
	s_waitcnt lgkmcnt(0)
	s_barrier
	ds_read2_b32 v[2:3], v37 offset1:129
	ds_read2_b32 v[4:5], v4 offset0:2 offset1:131
	ds_read2_b32 v[6:7], v6 offset0:4 offset1:133
	v_add_u32_e32 v8, 0xc00, v37
	ds_read2_b32 v[8:9], v8 offset0:6 offset1:135
	v_add_u32_e32 v10, 0x4000, v37
	ds_read2_b32 v[10:11], v10 offset0:32 offset1:161
	s_waitcnt lgkmcnt(4)
	v_cvt_pk_bf16_f32 v2, v2, v3
	s_waitcnt lgkmcnt(3)
	v_cvt_pk_bf16_f32 v3, v4, v5
	s_waitcnt lgkmcnt(2)
	v_cvt_pk_bf16_f32 v4, v6, v7
	v_add_u32_e32 v7, 0x4400, v37
	s_waitcnt lgkmcnt(1)
	v_cvt_pk_bf16_f32 v5, v8, v9
	ds_read2_b32 v[8:9], v7 offset0:34 offset1:163
	v_add_u32_e32 v7, 0x4800, v37
	s_waitcnt lgkmcnt(1)
	v_cvt_pk_bf16_f32 v6, v10, v11
	ds_read2_b32 v[10:11], v7 offset0:36 offset1:165
	v_add_u32_e32 v7, 0x4c00, v37
	ds_read2_b32 v[12:13], v7 offset0:38 offset1:167
	v_cvt_f32_ubyte0_e32 v7, s10
	v_rcp_iflag_f32_e32 v14, v7
	s_waitcnt lgkmcnt(2)
	v_cvt_pk_bf16_f32 v7, v8, v9
	s_waitcnt lgkmcnt(1)
	v_cvt_pk_bf16_f32 v8, v10, v11
	s_add_u32 s4, s30, s4
	v_mul_f32_e32 v10, 0x4f7ffffe, v14
	v_cvt_u32_f32_e32 v10, v10
	s_addc_u32 s5, s31, s5
	s_and_b32 s8, s14, 13
	s_cmp_eq_u32 s8, 1
	s_cselect_b32 s9, s22, 0x400
	s_sub_i32 s13, 0, s10
	v_readfirstlane_b32 s14, v10
	s_mul_i32 s13, s13, s14
	s_add_i32 s8, s11, s26
	s_mul_hi_u32 s13, s14, s13
	s_abs_i32 s12, s8
	s_add_i32 s14, s14, s13
	s_mul_hi_u32 s13, s12, s14
	s_mul_i32 s14, s13, s10
	s_sub_i32 s12, s12, s14
	s_ashr_i32 s11, s8, 31
	s_add_i32 s14, s13, 1
	s_sub_i32 s15, s12, s10
	s_cmp_ge_u32 s12, s10
	s_cselect_b32 s13, s14, s13
	s_cselect_b32 s12, s15, s12
	s_add_i32 s14, s13, 1
	s_cmp_ge_u32 s12, s10
	s_cselect_b32 s12, s14, s13
	s_xor_b32 s12, s12, s11
	s_sub_i32 s11, s12, s11
	s_mul_i32 s10, s10, s11
	s_sub_i32 s10, s8, s10
	v_lshl_add_u32 v10, s10, 7, v36
	s_lshl_b32 s8, s11, 6
	v_mad_i64_i32 v[10:11], s[10:11], s9, v10, 0
	v_lshl_add_u64 v[10:11], v[10:11], 1, s[4:5]
	s_ashr_i32 s9, s8, 31
	v_lshl_add_u64 v[10:11], s[8:9], 1, v[10:11]
	s_waitcnt lgkmcnt(0)
	v_cvt_pk_bf16_f32 v9, v12, v13
	v_lshl_add_u64 v[10:11], v[10:11], 0, v[0:1]
	s_add_i32 s26, s26, s34
	global_store_dwordx4 v[10:11], v[2:5], off
	global_store_dwordx4 v[10:11], v[6:9], off offset:64
	s_cmp_lg_u32 s2, s20
	s_waitcnt vmcnt(5)
	v_mov_b32_e32 v2, v22
	v_mov_b32_e32 v3, v23
	v_mov_b32_e32 v4, v24
	v_mov_b32_e32 v5, v25
	s_waitcnt vmcnt(4)
	v_mov_b32_e32 v6, v18
	v_mov_b32_e32 v7, v19
	v_mov_b32_e32 v8, v20
	v_mov_b32_e32 v9, v21
	s_waitcnt vmcnt(3)
	v_mov_b32_e32 v10, v30
	v_mov_b32_e32 v11, v31
	v_mov_b32_e32 v12, v32
	v_mov_b32_e32 v13, v33
	s_waitcnt vmcnt(2)
	v_mov_b32_e32 v14, v26
	v_mov_b32_e32 v15, v27
	v_mov_b32_e32 v16, v28
	v_mov_b32_e32 v17, v29
	s_barrier
	s_cbranch_scc0 .LBB0_691

; #define LAS __attribute__((address_space(3)))
; __device__ __forceinline__ void cvt_load(const Frame& F, const CvtMat& m, int tt, f32x4 (&v)[4]) {
;     const int nb = m.N >> 7, kb = tt / nb, nbk = tt - kb * nb, k0 = kb * 64, n0 = nbk * 128;
;     const int src = srccol(m.kind, n0 + (F.tid & 31) * 4);
; #pragma unroll
;     for (int i = 0; i < 4; ++i) v[i] = *(const f32x4*)(m.W + (size_t)(k0 + (F.tid >> 5) + 16 * i) * m.N + src);
; }
; __device__ __forceinline__ void cvt_store(const Frame& F, const CvtMat& m, int tt, const f32x4 (&v)[4]) {
;     LAS float* tile = (LAS float*)F.lds;
;     const int nb = m.N >> 7, kb = tt / nb, nbk = tt - kb * nb, k0 = kb * 64, n0 = nbk * 128;
;     const int tid = F.tid;
; #pragma unroll
;     for (int i = 0; i < 4; ++i) {
;         const int kk = (tid >> 5) + 16 * i, nn = (tid & 31) * 4;
;         tile[kk * 129 + nn] = v[i][0]; tile[kk * 129 + nn + 1] = v[i][1]; tile[kk * 129 + nn + 2] = v[i][2]; tile[kk * 129 + nn + 3] = v[i][3];
;     }
;     __syncthreads();
;     {
;         const int n = tid >> 2, ks = (tid & 3) * 16;
;         u32x4 o0, o1;
; #pragma unroll
;         for (int i = 0; i < 4; ++i) o0[i] = pk2(tile[(ks + 2 * i) * 129 + n], tile[(ks + 2 * i + 1) * 129 + n]);
; #pragma unroll
;         for (int i = 0; i < 4; ++i) o1[i] = pk2(tile[(ks + 8 + 2 * i) * 129 + n], tile[(ks + 8 + 2 * i + 1) * 129 + n]);
;         bf16_t* dst = m.Bt + (size_t)(n0 + n) * m.K + k0 + ks;
;         *(u32x4*)dst = o0; *(u32x4*)(dst + 8) = o1;
;     }
;     __syncthreads();
; }
; __device__ __forceinline__ void convert_layer(const Args& A, Frame& F, int l) {
;     refresh(F);
;     constexpr int NT = 2 * 16 * 44 + 2 * 44 * 8 + 16 * 56 + 3 * 16 * 8;
;     const int nmy = (NT - F.bid + F.G - 1) / F.G;
;     f32x4 v[4];
;     { CvtMat m; int tt; cvt_pick(A, F, l, F.bid, m, tt); cvt_load(F, m, tt, v); }
;     for (int j = 0; j < nmy; ++j) {
;         const int it = F.bid + j * F.G, itn = (j + 1 < nmy) ? it + F.G : it;
;         f32x4 vn[4];
;         { CvtMat mn; int ttn; cvt_pick(A, F, l, itn, mn, ttn); cvt_load(F, mn, ttn, vn); }
;         { CvtMat m; int tt; cvt_pick(A, F, l, it, m, tt); cvt_store(F, m, tt, v); }
; #pragma unroll
;         for (int i = 0; i < 4; ++i) v[i] = vn[i];
;     }
.LBB0_777:
	s_abs_i32 s6, s34
	v_cvt_f32_u32_e32 v3, s6
	s_ashr_i32 s18, s2, 6
	s_sub_i32 s2, s34, s38
	s_add_i32 s7, s2, 0xd3f
	v_rcp_iflag_f32_e32 v3, v3
	s_sub_i32 s2, 0xfffff2c1, s2
	s_xor_b32 s9, s7, s34
	s_sub_i32 s8, 0, s6
	v_mul_f32_e32 v3, 0x4f7ffffe, v3
	v_cvt_u32_f32_e32 v3, v3
	s_max_i32 s2, s7, s2
	s_ashr_i32 s7, s9, 31
	v_and_b32_e32 v142, 63, v0
	v_readfirstlane_b32 s9, v3
	s_mul_i32 s8, s8, s9
	s_mul_hi_u32 s8, s9, s8
	s_add_i32 s9, s9, s8
	s_mul_hi_u32 s8, s2, s9
	s_mul_i32 s9, s8, s6
	s_sub_i32 s2, s2, s9
	s_add_i32 s11, s8, 1
	s_sub_i32 s9, s2, s6
	s_cmp_ge_u32 s2, s6
	s_cselect_b32 s8, s11, s8
	s_cselect_b32 s2, s9, s2
	s_add_i32 s9, s8, 1
	s_cmp_ge_u32 s2, s6
	s_cselect_b32 s2, s9, s8
	s_xor_b32 s2, s2, s7
	s_sub_i32 s2, s2, s7
	s_cmp_lt_i32 s2, 1
	s_cbranch_scc1 .LBB0_857
	v_ashrrev_i32_e32 v35, 5, v0
	v_lshl_add_u32 v14, s10, 6, v35
	v_mad_i64_i32 v[4:5], s[6:7], v14, s12, 0
	v_ashrrev_i32_e32 v3, 31, v2
	s_waitcnt lgkmcnt(0)
	v_lshl_add_u64 v[4:5], v[4:5], 2, s[4:5]
	v_lshlrev_b64 v[10:11], 2, v[2:3]
	v_lshl_add_u64 v[2:3], v[4:5], 0, v[10:11]
	v_add_u32_e32 v4, 16, v14
	v_add_u32_e32 v12, 32, v14
	v_add_u32_e32 v14, 48, v14
	v_mad_i64_i32 v[4:5], s[6:7], s12, v4, 0
	v_mad_i64_i32 v[12:13], s[6:7], s12, v12, 0
	v_mad_i64_i32 v[14:15], s[6:7], s12, v14, 0
	v_lshl_add_u64 v[4:5], v[4:5], 2, s[4:5]
	v_lshl_add_u64 v[12:13], v[12:13], 2, s[4:5]
	v_lshl_add_u64 v[14:15], v[14:15], 2, s[4:5]
	v_lshl_add_u64 v[6:7], v[4:5], 0, v[10:11]
	v_lshl_add_u64 v[12:13], v[12:13], 0, v[10:11]
	v_lshl_add_u64 v[14:15], v[14:15], 0, v[10:11]
	global_load_dwordx4 v[2:5], v[2:3], off
	s_nop 0
	global_load_dwordx4 v[6:9], v[6:7], off
	s_nop 0
	global_load_dwordx4 v[10:13], v[12:13], off
	s_nop 0
	global_load_dwordx4 v[14:17], v[14:15], off
	v_lshlrev_b32_e32 v22, 3, v0
	v_and_b32_e32 v22, 24, v22
	v_ashrrev_i32_e32 v36, 2, v0
	v_mul_u32_u24_e32 v25, 0x204, v22
	v_and_b32_e32 v0, -4, v0
	v_add3_u32 v37, 0, v25, v0
	v_lshrrev_b32_e32 v0, 1, v18
	s_movk_i32 s4, 0x204
	v_and_b32_e32 v0, 16, v0
	v_lshl_add_u32 v23, v34, 2, 0
	v_mul_lo_u32 v24, v35, s4
	v_and_or_b32 v38, v21, 32, v0
	v_and_b32_e32 v0, 0x60, v18
	v_or_b32_e32 v39, v20, v19
	v_or3_b32 v40, v0, v19, v20
	s_mov_b32 s12, 0
	v_add_u32_e32 v41, v23, v24
	v_lshlrev_b32_e32 v0, 1, v22
	s_branch .LBB0_780
.LBB0_779:
	s_waitcnt vmcnt(7)
	ds_write2_b32 v41, v2, v3 offset1:1
	ds_write2_b32 v41, v4, v5 offset0:2 offset1:3
	v_add_u32_e32 v2, 0x2040, v41
	s_waitcnt vmcnt(6)
	ds_write2_b32 v2, v6, v7 offset1:1
	v_add_u32_e32 v2, 0x2048, v41
	ds_write2_b32 v2, v8, v9 offset1:1
	v_add_u32_e32 v2, 0x4080, v41
	s_waitcnt vmcnt(5)
	ds_write2_b32 v2, v10, v11 offset1:1
	v_add_u32_e32 v2, 0x4088, v41
	ds_write2_b32 v2, v12, v13 offset1:1
	v_add_u32_e32 v2, 0x60c0, v41
	s_waitcnt vmcnt(4)
	ds_write2_b32 v2, v14, v15 offset1:1
	v_add_u32_e32 v2, 0x60c8, v41
	v_add_u32_e32 v4, 0x400, v37
	v_add_u32_e32 v6, 0x800, v37
	ds_write2_b32 v2, v16, v17 offset1:1
	s_waitcnt lgkmcnt(0)
	s_barrier
	ds_read2_b32 v[2:3], v37 offset1:129
	ds_read2_b32 v[4:5], v4 offset0:2 offset1:131
	ds_read2_b32 v[6:7], v6 offset0:4 offset1:133
	v_add_u32_e32 v8, 0xc00, v37
	ds_read2_b32 v[8:9], v8 offset0:6 offset1:135
	v_add_u32_e32 v10, 0x4000, v37
	ds_read2_b32 v[10:11], v10 offset0:32 offset1:161
	s_waitcnt lgkmcnt(4)
	v_cvt_pk_bf16_f32 v2, v2, v3
	s_waitcnt lgkmcnt(3)
	v_cvt_pk_bf16_f32 v3, v4, v5
	s_waitcnt lgkmcnt(2)
	v_cvt_pk_bf16_f32 v4, v6, v7
	v_add_u32_e32 v7, 0x4400, v37
	s_waitcnt lgkmcnt(1)
	v_cvt_pk_bf16_f32 v5, v8, v9
	ds_read2_b32 v[8:9], v7 offset0:34 offset1:163
	v_add_u32_e32 v7, 0x4800, v37
	s_waitcnt lgkmcnt(1)
	v_cvt_pk_bf16_f32 v6, v10, v11
	ds_read2_b32 v[10:11], v7 offset0:36 offset1:165
	v_add_u32_e32 v7, 0x4c00, v37
	ds_read2_b32 v[12:13], v7 offset0:38 offset1:167
	v_cvt_f32_ubyte0_e32 v7, s8
	v_rcp_iflag_f32_e32 v14, v7
	s_waitcnt lgkmcnt(2)
	v_cvt_pk_bf16_f32 v7, v8, v9
	s_waitcnt lgkmcnt(1)
	v_cvt_pk_bf16_f32 v8, v10, v11
	s_add_u32 s4, s30, s4
	v_mul_f32_e32 v10, 0x4f7ffffe, v14
	v_cvt_u32_f32_e32 v10, v10
	s_addc_u32 s5, s31, s5
	s_and_b32 s6, s13, 13
	s_cmp_eq_u32 s6, 1
	s_cselect_b32 s7, s22, 0x400
	s_sub_i32 s11, 0, s8
	v_readfirstlane_b32 s13, v10
	s_mul_i32 s11, s11, s13
	s_add_i32 s6, s9, s38
	s_mul_hi_u32 s11, s13, s11
	s_abs_i32 s10, s6
	s_add_i32 s13, s13, s11
	s_mul_hi_u32 s11, s10, s13
	s_mul_i32 s13, s11, s8
	s_sub_i32 s10, s10, s13
	s_ashr_i32 s9, s6, 31
	s_add_i32 s13, s11, 1
	s_sub_i32 s14, s10, s8
	s_cmp_ge_u32 s10, s8
	s_cselect_b32 s11, s13, s11
	s_cselect_b32 s10, s14, s10
	s_add_i32 s13, s11, 1
	s_cmp_ge_u32 s10, s8
	s_cselect_b32 s10, s13, s11
	s_xor_b32 s10, s10, s9
	s_sub_i32 s9, s10, s9
	s_mul_i32 s8, s8, s9
	s_sub_i32 s8, s6, s8
	v_lshl_add_u32 v10, s8, 7, v36
	s_lshl_b32 s6, s9, 6
	v_mad_i64_i32 v[10:11], s[8:9], s7, v10, 0
	v_lshl_add_u64 v[10:11], v[10:11], 1, s[4:5]
	s_ashr_i32 s7, s6, 31
	v_lshl_add_u64 v[10:11], s[6:7], 1, v[10:11]
	s_waitcnt lgkmcnt(0)
	v_cvt_pk_bf16_f32 v9, v12, v13
	v_lshl_add_u64 v[10:11], v[10:11], 0, v[0:1]
	s_add_i32 s38, s38, s34
	global_store_dwordx4 v[10:11], v[2:5], off
	global_store_dwordx4 v[10:11], v[6:9], off offset:64
	s_cmp_eq_u32 s2, s12
	s_waitcnt vmcnt(5)
	v_mov_b32_e32 v2, v22
	v_mov_b32_e32 v3, v23
	v_mov_b32_e32 v4, v24
	v_mov_b32_e32 v5, v25
	s_waitcnt vmcnt(4)
	v_mov_b32_e32 v6, v18
	v_mov_b32_e32 v7, v19
	v_mov_b32_e32 v8, v20
	v_mov_b32_e32 v9, v21
	s_waitcnt vmcnt(3)
	v_mov_b32_e32 v10, v30
	v_mov_b32_e32 v11, v31
	v_mov_b32_e32 v12, v32
	v_mov_b32_e32 v13, v33
	s_waitcnt vmcnt(2)
	v_mov_b32_e32 v14, v26
	v_mov_b32_e32 v15, v27
	v_mov_b32_e32 v16, v28
	v_mov_b32_e32 v17, v29
	s_barrier
	s_cbranch_scc1 .LBB0_857
